# v18 plus: in the 4 light load segments per K-iteration the fragment-read wait is taken before the s_barrier instead of after it
# baseline (speedup 1.0000x reference)
; #define PG8_STAGE(bufoff, gbase, voff) do { _Pragma("unroll") for (int _i = 0; _i < 2; ++_i) \
;         __builtin_amdgcn_global_load_lds((const unsigned*)((const char*)(gbase) + (voff)[_i]), (LAS unsigned*)(lds + (bufoff) + ldsw + _i * 8192), 16, 0, 0); } while (0)
; #define PG8_LDA(dst, b, h) do { _Pragma("unroll") for (int m = 0; m < 4; ++m) _Pragma("unroll") for (int k = 0; k < 2; ++k) dst[m][k] = *(const LAS bf16x8*)(lds + PG8_SA(b, h) + aoff + m * 2048 + k * 1024); } while (0)
; #define PG8_LDB(dst, b, h) do { _Pragma("unroll") for (int n = 0; n < 2; ++n) _Pragma("unroll") for (int k = 0; k < 2; ++k) dst[n][k] = *(const LAS bf16x8*)(lds + PG8_SB(b, h) + boff + n * 2048 + k * 1024); } while (0)
; #define PG8_MMA(ai, bj, At, Bt) do { __builtin_amdgcn_s_setprio(1); _Pragma("unroll") for (int m = 0; m < 4; ++m) _Pragma("unroll") for (int n = 0; n < 2; ++n) _Pragma("unroll") for (int k = 0; k < 2; ++k) \
;         acc[ai][bj][m][n] = __builtin_amdgcn_mfma_f32_16x16x32_bf16(Bt[n][k], At[m][k], acc[ai][bj][m][n], 0, 0, 0); __builtin_amdgcn_s_setprio(0); } while (0)
; #define PG8_WAIT_V(n) asm volatile("s_waitcnt vmcnt(" #n ")" ::: "memory")
; #define PG8_WAIT_L(n) asm volatile("s_waitcnt lgkmcnt(" #n ")" ::: "memory")
; #define PG8_BAR __builtin_amdgcn_s_barrier()
; template <class Epi, class Sched>
; __device__ __forceinline__ void gemm_phase(LAS unsigned char* lds, const Gemm g, const Sched& S, const Epi& E) {
;     ...
;             const bool last = (t == nt - 2);
;             const char* a1 = cA + (size_t)(t + 1) * kstep;
;             const char* a2 = last ? nA : cA + (size_t)(t + 2) * kstep; const char* b2 = last ? nB : cB + (size_t)(t + 2) * kstep;
;             const char* a3 = a2 + kstep; const char* b3 = b2 + kstep;
;             PG8_LDB(B0, 0, 0); PG8_SCHED; PG8_LDA(At, 0, 0); PG8_STAGE(PG8_SA(1, 1), a1 + hstep, voffA);
;             PG8_WAIT_L(8); PG8_BAR; PG8_WAIT_L(0); PG8_MMA(0, 0, At, B0); PG8_BAR; PG8_SCHED;
;             PG8_LDB(B1, 0, 1); PG8_STAGE(PG8_SB(0, 0), b2, voffB);
;             PG8_BAR; PG8_WAIT_L(0); PG8_MMA(0, 1, At, B1); PG8_BAR;
;             PG8_LDA(At, 0, 1); PG8_STAGE(PG8_SA(0, 0), a2, voffA);
;             PG8_BAR; PG8_WAIT_L(0); PG8_MMA(1, 0, At, B0); PG8_BAR; PG8_SCHED;
;             PG8_STAGE(PG8_SB(0, 1), b2 + hstep, voffB);
;             PG8_WAIT_V(6); PG8_BAR; PG8_MMA(1, 1, At, B1); PG8_BAR;
.LBB0_125:
	s_add_u32 s20, s16, 0xfff80080
	s_addc_u32 s21, s17, -1
	s_add_i32 s45, 0, 0x10000
	ds_read_b128 v[138:141], v129
	ds_read_b128 v[160:163], v129 offset:1024
	ds_read_b128 v[164:167], v129 offset:2048
	ds_read_b128 v[168:171], v129 offset:3072
	s_cmp_eq_u32 s44, 28
	s_cselect_b32 s23, s7, s21
	s_cselect_b32 s22, s40, s20
	s_cselect_b32 s21, s5, s43
	s_cselect_b32 s20, s41, s42
	s_add_i32 m0, s30, 0xc000
	ds_read_b128 v[172:175], v145
	ds_read_b128 v[200:203], v145 offset:1024
	ds_read_b128 v[204:207], v145 offset:2048
	ds_read_b128 v[208:211], v145 offset:3072
	ds_read_b128 v[212:215], v145 offset:4096
	ds_read_b128 v[216:219], v145 offset:5120
	ds_read_b128 v[220:223], v145 offset:6144
	ds_read_b128 v[224:227], v145 offset:7168
	global_load_lds_dwordx4 v134, s[16:17]
	s_add_i32 m0, s30, 0xe000
	s_nop 0
	global_load_lds_dwordx4 v136, s[16:17]
	s_waitcnt lgkmcnt(8)
	s_barrier
	s_waitcnt lgkmcnt(0)
	v_mfma_f32_16x16x32_bf16 v[124:127], v[138:141], v[172:175], v[124:127]
	v_mfma_f32_16x16x32_bf16 v[120:123], v[164:167], v[172:175], v[120:123]
	v_mfma_f32_16x16x32_bf16 v[116:119], v[138:141], v[204:207], v[116:119]
	v_mfma_f32_16x16x32_bf16 v[108:111], v[164:167], v[204:207], v[108:111]
	v_mfma_f32_16x16x32_bf16 v[100:103], v[138:141], v[212:215], v[100:103]
	v_mfma_f32_16x16x32_bf16 v[92:95], v[164:167], v[212:215], v[92:95]
	v_mfma_f32_16x16x32_bf16 v[84:87], v[138:141], v[220:223], v[84:87]
	v_mfma_f32_16x16x32_bf16 v[76:79], v[164:167], v[220:223], v[76:79]
	v_mfma_f32_16x16x32_bf16 v[124:127], v[160:163], v[200:203], v[124:127]
	v_mfma_f32_16x16x32_bf16 v[120:123], v[168:171], v[200:203], v[120:123]
	v_mfma_f32_16x16x32_bf16 v[116:119], v[160:163], v[208:211], v[116:119]
	v_mfma_f32_16x16x32_bf16 v[108:111], v[168:171], v[208:211], v[108:111]
	v_mfma_f32_16x16x32_bf16 v[100:103], v[160:163], v[216:219], v[100:103]
	v_mfma_f32_16x16x32_bf16 v[92:95], v[168:171], v[216:219], v[92:95]
	v_mfma_f32_16x16x32_bf16 v[84:87], v[160:163], v[224:227], v[84:87]
	v_mfma_f32_16x16x32_bf16 v[76:79], v[168:171], v[224:227], v[76:79]
	s_barrier
	s_add_i32 s48, 0, 0x14000
	s_add_i32 s45, s45, s29
	ds_read_b128 v[228:231], v129 offset:16384
	ds_read_b128 v[232:235], v129 offset:17408
	ds_read_b128 v[236:239], v129 offset:18432
	ds_read_b128 v[240:243], v129 offset:19456
	s_add_u32 s84, s20, 0x80
	s_addc_u32 s85, s21, 0
	s_mov_b32 m0, s45
	s_nop 0
	global_load_lds_dwordx4 v148, s[20:21]
	s_add_i32 m0, s45, 0x2000
	s_nop 0
	global_load_lds_dwordx4 v128, s[20:21]
	s_waitcnt lgkmcnt(0)
	s_barrier
	v_mfma_f32_16x16x32_bf16 v[112:115], v[228:231], v[172:175], v[112:115]
	v_mfma_f32_16x16x32_bf16 v[104:107], v[236:239], v[172:175], v[104:107]
	v_mfma_f32_16x16x32_bf16 v[96:99], v[228:231], v[204:207], v[96:99]
	v_mfma_f32_16x16x32_bf16 v[88:91], v[236:239], v[204:207], v[88:91]
	v_mfma_f32_16x16x32_bf16 v[80:83], v[228:231], v[212:215], v[80:83]
	v_mfma_f32_16x16x32_bf16 v[72:75], v[236:239], v[212:215], v[72:75]
	v_mfma_f32_16x16x32_bf16 v[68:71], v[228:231], v[220:223], v[68:71]
	v_mfma_f32_16x16x32_bf16 v[64:67], v[236:239], v[220:223], v[64:67]
	v_mfma_f32_16x16x32_bf16 v[112:115], v[232:235], v[200:203], v[112:115]
	v_mfma_f32_16x16x32_bf16 v[104:107], v[240:243], v[200:203], v[104:107]
	v_mfma_f32_16x16x32_bf16 v[96:99], v[232:235], v[208:211], v[96:99]
	v_mfma_f32_16x16x32_bf16 v[88:91], v[240:243], v[208:211], v[88:91]
	v_mfma_f32_16x16x32_bf16 v[80:83], v[232:235], v[216:219], v[80:83]
	v_mfma_f32_16x16x32_bf16 v[72:75], v[240:243], v[216:219], v[72:75]
	v_mfma_f32_16x16x32_bf16 v[68:71], v[232:235], v[224:227], v[68:71]
	v_mfma_f32_16x16x32_bf16 v[64:67], v[240:243], v[224:227], v[64:67]
	s_mov_b32 m0, s30
	s_add_u32 s86, s22, 0x80
	s_addc_u32 s87, s23, 0
	s_barrier
	ds_read_b128 v[172:175], v145 offset:16384
	ds_read_b128 v[200:203], v145 offset:17408
	ds_read_b128 v[204:207], v145 offset:18432
	ds_read_b128 v[208:211], v145 offset:19456
	ds_read_b128 v[212:215], v145 offset:20480
	ds_read_b128 v[216:219], v145 offset:21504
	ds_read_b128 v[220:223], v145 offset:22528
	ds_read_b128 v[224:227], v145 offset:23552
	global_load_lds_dwordx4 v132, s[22:23]
	s_mov_b32 m0, s31
	s_nop 0
	global_load_lds_dwordx4 v130, s[22:23]
	s_waitcnt lgkmcnt(0)
	s_barrier
	v_mfma_f32_16x16x32_bf16 v[60:63], v[138:141], v[172:175], v[60:63]
	v_mfma_f32_16x16x32_bf16 v[56:59], v[164:167], v[172:175], v[56:59]
	v_mfma_f32_16x16x32_bf16 v[52:55], v[138:141], v[204:207], v[52:55]
	v_mfma_f32_16x16x32_bf16 v[44:47], v[164:167], v[204:207], v[44:47]
	v_mfma_f32_16x16x32_bf16 v[36:39], v[138:141], v[212:215], v[36:39]
	v_mfma_f32_16x16x32_bf16 v[28:31], v[164:167], v[212:215], v[28:31]
	v_mfma_f32_16x16x32_bf16 v[20:23], v[138:141], v[220:223], v[20:23]
	v_mfma_f32_16x16x32_bf16 v[12:15], v[164:167], v[220:223], v[12:15]
	v_mfma_f32_16x16x32_bf16 v[60:63], v[160:163], v[200:203], v[60:63]
	v_mfma_f32_16x16x32_bf16 v[56:59], v[168:171], v[200:203], v[56:59]
	v_mfma_f32_16x16x32_bf16 v[52:55], v[160:163], v[208:211], v[52:55]
	v_mfma_f32_16x16x32_bf16 v[44:47], v[168:171], v[208:211], v[44:47]
	v_mfma_f32_16x16x32_bf16 v[36:39], v[160:163], v[216:219], v[36:39]
	v_mfma_f32_16x16x32_bf16 v[28:31], v[168:171], v[216:219], v[28:31]
	v_mfma_f32_16x16x32_bf16 v[20:23], v[160:163], v[224:227], v[20:23]
	v_mfma_f32_16x16x32_bf16 v[12:15], v[168:171], v[224:227], v[12:15]
	s_barrier
	s_add_u32 s46, s20, 0x80000
	s_addc_u32 s47, s21, 0
	s_add_i32 s45, s48, s29
	s_mov_b32 m0, s45
	s_nop 0
	global_load_lds_dwordx4 v148, s[46:47]
	s_add_i32 m0, s45, 0x2000
	s_nop 0
	global_load_lds_dwordx4 v128, s[46:47]
	s_waitcnt vmcnt(6)
	s_barrier
; #define PG8_STAGE(bufoff, gbase, voff) do { _Pragma("unroll") for (int _i = 0; _i < 2; ++_i) \
;         __builtin_amdgcn_global_load_lds((const unsigned*)((const char*)(gbase) + (voff)[_i]), (LAS unsigned*)(lds + (bufoff) + ldsw + _i * 8192), 16, 0, 0); } while (0)
; #define PG8_LDA(dst, b, h) do { _Pragma("unroll") for (int m = 0; m < 4; ++m) _Pragma("unroll") for (int k = 0; k < 2; ++k) dst[m][k] = *(const LAS bf16x8*)(lds + PG8_SA(b, h) + aoff + m * 2048 + k * 1024); } while (0)
; #define PG8_LDB(dst, b, h) do { _Pragma("unroll") for (int n = 0; n < 2; ++n) _Pragma("unroll") for (int k = 0; k < 2; ++k) dst[n][k] = *(const LAS bf16x8*)(lds + PG8_SB(b, h) + boff + n * 2048 + k * 1024); } while (0)
; #define PG8_MMA(ai, bj, At, Bt) do { __builtin_amdgcn_s_setprio(1); _Pragma("unroll") for (int m = 0; m < 4; ++m) _Pragma("unroll") for (int n = 0; n < 2; ++n) _Pragma("unroll") for (int k = 0; k < 2; ++k) \
;         acc[ai][bj][m][n] = __builtin_amdgcn_mfma_f32_16x16x32_bf16(Bt[n][k], At[m][k], acc[ai][bj][m][n], 0, 0, 0); __builtin_amdgcn_s_setprio(0); } while (0)
; #define PG8_WAIT_V(n) asm volatile("s_waitcnt vmcnt(" #n ")" ::: "memory")
; #define PG8_WAIT_L(n) asm volatile("s_waitcnt lgkmcnt(" #n ")" ::: "memory")
; #define PG8_BAR __builtin_amdgcn_s_barrier()
; #define PG8_SCHED __builtin_amdgcn_sched_barrier(0)
; template <class Epi, class Sched>
; __device__ __forceinline__ void gemm_phase(LAS unsigned char* lds, const Gemm g, const Sched& S, const Epi& E) {
;     ...
;             PG8_WAIT_V(6); PG8_BAR; PG8_MMA(1, 1, At, B1); PG8_BAR;
;             PG8_LDB(B0, 1, 0); PG8_SCHED; PG8_LDA(At, 1, 0); PG8_STAGE(PG8_SA(0, 1), a2 + hstep, voffA);
;             PG8_WAIT_L(8); PG8_BAR; PG8_WAIT_L(0); PG8_MMA(0, 0, At, B0); PG8_BAR; PG8_SCHED;
;             PG8_LDB(B1, 1, 1); PG8_STAGE(PG8_SB(1, 0), b3, voffB);
;             PG8_BAR; PG8_WAIT_L(0); PG8_MMA(0, 1, At, B1); PG8_BAR;
;             PG8_LDA(At, 1, 1); PG8_STAGE(PG8_SA(1, 0), a3, voffA);
;             PG8_BAR; PG8_WAIT_L(0); PG8_MMA(1, 0, At, B0); PG8_BAR; PG8_SCHED;
	v_mfma_f32_16x16x32_bf16 v[48:51], v[228:231], v[172:175], v[48:51]
	v_mfma_f32_16x16x32_bf16 v[40:43], v[236:239], v[172:175], v[40:43]
	v_mfma_f32_16x16x32_bf16 v[32:35], v[228:231], v[204:207], v[32:35]
	v_mfma_f32_16x16x32_bf16 v[24:27], v[236:239], v[204:207], v[24:27]
	v_mfma_f32_16x16x32_bf16 v[16:19], v[228:231], v[212:215], v[16:19]
	v_mfma_f32_16x16x32_bf16 v[8:11], v[236:239], v[212:215], v[8:11]
	v_mfma_f32_16x16x32_bf16 v[4:7], v[228:231], v[220:223], v[4:7]
	v_mfma_f32_16x16x32_bf16 v[0:3], v[236:239], v[220:223], v[0:3]
	v_mfma_f32_16x16x32_bf16 v[48:51], v[232:235], v[200:203], v[48:51]
	v_mfma_f32_16x16x32_bf16 v[40:43], v[240:243], v[200:203], v[40:43]
	v_mfma_f32_16x16x32_bf16 v[32:35], v[232:235], v[208:211], v[32:35]
	v_mfma_f32_16x16x32_bf16 v[24:27], v[240:243], v[208:211], v[24:27]
	v_mfma_f32_16x16x32_bf16 v[16:19], v[232:235], v[216:219], v[16:19]
	v_mfma_f32_16x16x32_bf16 v[8:11], v[240:243], v[216:219], v[8:11]
	v_mfma_f32_16x16x32_bf16 v[4:7], v[232:235], v[224:227], v[4:7]
	v_mfma_f32_16x16x32_bf16 v[0:3], v[240:243], v[224:227], v[0:3]
	s_add_i32 s45, 0, 0x18000
	s_barrier
	ds_read_b128 v[138:141], v129 offset:32768
	ds_read_b128 v[160:163], v129 offset:33792
	ds_read_b128 v[164:167], v129 offset:34816
	ds_read_b128 v[168:171], v129 offset:35840
	s_add_u32 s22, s22, 0x80000
	s_addc_u32 s23, s23, 0
	s_mov_b32 m0, s33
	ds_read_b128 v[172:175], v145 offset:32768
	ds_read_b128 v[200:203], v145 offset:33792
	ds_read_b128 v[204:207], v145 offset:34816
	ds_read_b128 v[208:211], v145 offset:35840
	ds_read_b128 v[212:215], v145 offset:36864
	ds_read_b128 v[216:219], v145 offset:37888
	ds_read_b128 v[220:223], v145 offset:38912
	ds_read_b128 v[224:227], v145 offset:39936
	global_load_lds_dwordx4 v132, s[22:23]
	s_mov_b32 m0, s34
	s_nop 0
	global_load_lds_dwordx4 v130, s[22:23]
	s_waitcnt lgkmcnt(8)
	s_barrier
	s_waitcnt lgkmcnt(0)
	v_mfma_f32_16x16x32_bf16 v[124:127], v[138:141], v[172:175], v[124:127]
	v_mfma_f32_16x16x32_bf16 v[120:123], v[164:167], v[172:175], v[120:123]
	v_mfma_f32_16x16x32_bf16 v[116:119], v[138:141], v[204:207], v[116:119]
	v_mfma_f32_16x16x32_bf16 v[108:111], v[164:167], v[204:207], v[108:111]
	v_mfma_f32_16x16x32_bf16 v[100:103], v[138:141], v[212:215], v[100:103]
	v_mfma_f32_16x16x32_bf16 v[92:95], v[164:167], v[212:215], v[92:95]
	v_mfma_f32_16x16x32_bf16 v[84:87], v[138:141], v[220:223], v[84:87]
	v_mfma_f32_16x16x32_bf16 v[76:79], v[164:167], v[220:223], v[76:79]
	v_mfma_f32_16x16x32_bf16 v[124:127], v[160:163], v[200:203], v[124:127]
	v_mfma_f32_16x16x32_bf16 v[120:123], v[168:171], v[200:203], v[120:123]
	v_mfma_f32_16x16x32_bf16 v[116:119], v[160:163], v[208:211], v[116:119]
	v_mfma_f32_16x16x32_bf16 v[108:111], v[168:171], v[208:211], v[108:111]
	v_mfma_f32_16x16x32_bf16 v[100:103], v[160:163], v[216:219], v[100:103]
	v_mfma_f32_16x16x32_bf16 v[92:95], v[168:171], v[216:219], v[92:95]
	v_mfma_f32_16x16x32_bf16 v[84:87], v[160:163], v[224:227], v[84:87]
	v_mfma_f32_16x16x32_bf16 v[76:79], v[168:171], v[224:227], v[76:79]
	s_barrier
	s_add_i32 s22, 0, 0x1c000
	s_add_i32 s23, s45, s29
	s_mov_b32 m0, s23
	ds_read_b128 v[228:231], v129 offset:49152
	ds_read_b128 v[232:235], v129 offset:50176
	ds_read_b128 v[236:239], v129 offset:51200
	ds_read_b128 v[240:243], v129 offset:52224
	global_load_lds_dwordx4 v148, s[84:85]
	s_add_i32 m0, s23, 0x2000
	s_nop 0
	global_load_lds_dwordx4 v128, s[84:85]
	s_waitcnt lgkmcnt(0)
	s_barrier
	v_mfma_f32_16x16x32_bf16 v[112:115], v[228:231], v[172:175], v[112:115]
	v_mfma_f32_16x16x32_bf16 v[104:107], v[236:239], v[172:175], v[104:107]
	v_mfma_f32_16x16x32_bf16 v[96:99], v[228:231], v[204:207], v[96:99]
	v_mfma_f32_16x16x32_bf16 v[88:91], v[236:239], v[204:207], v[88:91]
	v_mfma_f32_16x16x32_bf16 v[80:83], v[228:231], v[212:215], v[80:83]
	v_mfma_f32_16x16x32_bf16 v[72:75], v[236:239], v[212:215], v[72:75]
	v_mfma_f32_16x16x32_bf16 v[68:71], v[228:231], v[220:223], v[68:71]
	v_mfma_f32_16x16x32_bf16 v[64:67], v[236:239], v[220:223], v[64:67]
	v_mfma_f32_16x16x32_bf16 v[112:115], v[232:235], v[200:203], v[112:115]
	v_mfma_f32_16x16x32_bf16 v[104:107], v[240:243], v[200:203], v[104:107]
	v_mfma_f32_16x16x32_bf16 v[96:99], v[232:235], v[208:211], v[96:99]
	v_mfma_f32_16x16x32_bf16 v[88:91], v[240:243], v[208:211], v[88:91]
	v_mfma_f32_16x16x32_bf16 v[80:83], v[232:235], v[216:219], v[80:83]
	v_mfma_f32_16x16x32_bf16 v[72:75], v[240:243], v[216:219], v[72:75]
	v_mfma_f32_16x16x32_bf16 v[68:71], v[232:235], v[224:227], v[68:71]
	v_mfma_f32_16x16x32_bf16 v[64:67], v[240:243], v[224:227], v[64:67]
	s_mov_b32 m0, s35
	s_barrier
	ds_read_b128 v[172:175], v145 offset:49152
	ds_read_b128 v[200:203], v145 offset:50176
	ds_read_b128 v[204:207], v145 offset:51200
	ds_read_b128 v[208:211], v145 offset:52224
	ds_read_b128 v[212:215], v145 offset:53248
	ds_read_b128 v[216:219], v145 offset:54272
	ds_read_b128 v[220:223], v145 offset:55296
	ds_read_b128 v[224:227], v145 offset:56320
	global_load_lds_dwordx4 v132, s[86:87]
	s_mov_b32 m0, s36
	s_nop 0
	global_load_lds_dwordx4 v130, s[86:87]
	s_waitcnt lgkmcnt(0)
	s_barrier
	v_mfma_f32_16x16x32_bf16 v[60:63], v[138:141], v[172:175], v[60:63]
	v_mfma_f32_16x16x32_bf16 v[56:59], v[164:167], v[172:175], v[56:59]
	v_mfma_f32_16x16x32_bf16 v[52:55], v[138:141], v[204:207], v[52:55]
	v_mfma_f32_16x16x32_bf16 v[44:47], v[164:167], v[204:207], v[44:47]
	v_mfma_f32_16x16x32_bf16 v[36:39], v[138:141], v[212:215], v[36:39]
	v_mfma_f32_16x16x32_bf16 v[28:31], v[164:167], v[212:215], v[28:31]
	v_mfma_f32_16x16x32_bf16 v[20:23], v[138:141], v[220:223], v[20:23]
	v_mfma_f32_16x16x32_bf16 v[12:15], v[164:167], v[220:223], v[12:15]
	v_mfma_f32_16x16x32_bf16 v[60:63], v[160:163], v[200:203], v[60:63]
	v_mfma_f32_16x16x32_bf16 v[56:59], v[168:171], v[200:203], v[56:59]
	v_mfma_f32_16x16x32_bf16 v[52:55], v[160:163], v[208:211], v[52:55]
	v_mfma_f32_16x16x32_bf16 v[44:47], v[168:171], v[208:211], v[44:47]
	v_mfma_f32_16x16x32_bf16 v[36:39], v[160:163], v[216:219], v[36:39]
	v_mfma_f32_16x16x32_bf16 v[28:31], v[168:171], v[216:219], v[28:31]
	v_mfma_f32_16x16x32_bf16 v[20:23], v[160:163], v[224:227], v[20:23]
	v_mfma_f32_16x16x32_bf16 v[12:15], v[168:171], v[224:227], v[12:15]
	s_barrier
; __device__ __forceinline__ unsigned cvt_pk_bf16(float lo, float hi) { unsigned r; asm("v_cvt_pk_bf16_f32 %0, %1, %2" : "=v"(r) : "v"(lo), "v"(hi)); return r; }
; #define PG8_STAGE(bufoff, gbase, voff) do { _Pragma("unroll") for (int _i = 0; _i < 2; ++_i) \
;         __builtin_amdgcn_global_load_lds((const unsigned*)((const char*)(gbase) + (voff)[_i]), (LAS unsigned*)(lds + (bufoff) + ldsw + _i * 8192), 16, 0, 0); } while (0)
; #define PG8_MMA(ai, bj, At, Bt) do { __builtin_amdgcn_s_setprio(1); _Pragma("unroll") for (int m = 0; m < 4; ++m) _Pragma("unroll") for (int n = 0; n < 2; ++n) _Pragma("unroll") for (int k = 0; k < 2; ++k) \
;         acc[ai][bj][m][n] = __builtin_amdgcn_mfma_f32_16x16x32_bf16(Bt[n][k], At[m][k], acc[ai][bj][m][n], 0, 0, 0); __builtin_amdgcn_s_setprio(0); } while (0)
; #define PG8_WAIT_V(n) asm volatile("s_waitcnt vmcnt(" #n ")" ::: "memory")
; #define PG8_BAR __builtin_amdgcn_s_barrier()
;     __device__ __forceinline__ void operator()(const f32x4 (&acc)[2][2][4][2], const Unit& u, int wr, int wc, int fr, int fq) const {
;         const int row0 = u.pm * BM + wr * 64 + fr, col0 = u.pn * BM + wc * 32 + 8 * fq;
; #pragma unroll
;         for (int ai = 0; ai < 2; ++ai)
; #pragma unroll
;             for (int m = 0; m < 4; ++m) { bf16_t* rowp = O + (size_t)(row0 + ai * HALF + m * 16) * ldc + col0;
; #pragma unroll
;                 for (int bj = 0; bj < 2; ++bj) { const f32x4 v0 = acc[ai][bj][m][0], v1 = acc[ai][bj][m][1];
;                     u32x4 w; w.x = cvt_pk_bf16(v0[0], v0[1]); w.y = cvt_pk_bf16(v0[2], v0[3]); w.z = cvt_pk_bf16(v1[0], v1[1]); w.w = cvt_pk_bf16(v1[2], v1[3]);
;                     *(u32x4*)(rowp + bj * HALF) = w; } }
; template <class Epi, class Sched>
; __device__ __forceinline__ void gemm_phase(LAS unsigned char* lds, const Gemm g, const Sched& S, const Epi& E) {
;     ...
;             PG8_STAGE(PG8_SB(1, 1), b3 + hstep, voffB);
;             PG8_WAIT_V(6); PG8_BAR; PG8_MMA(1, 1, At, B1); PG8_BAR;
	s_add_u32 s20, s20, 0x80080
	s_addc_u32 s21, s21, 0
	s_add_i32 s22, s22, s29
	s_mov_b32 m0, s22
	s_nop 0
	global_load_lds_dwordx4 v148, s[20:21]
	s_add_i32 m0, s22, 0x2000
	s_nop 0
	global_load_lds_dwordx4 v128, s[20:21]
	s_waitcnt vmcnt(6)
	s_barrier
	v_mfma_f32_16x16x32_bf16 v[48:51], v[228:231], v[172:175], v[48:51]
	v_mfma_f32_16x16x32_bf16 v[40:43], v[236:239], v[172:175], v[40:43]
	v_mfma_f32_16x16x32_bf16 v[32:35], v[228:231], v[204:207], v[32:35]
	v_mfma_f32_16x16x32_bf16 v[24:27], v[236:239], v[204:207], v[24:27]
	v_mfma_f32_16x16x32_bf16 v[16:19], v[228:231], v[212:215], v[16:19]
	v_mfma_f32_16x16x32_bf16 v[8:11], v[236:239], v[212:215], v[8:11]
	v_mfma_f32_16x16x32_bf16 v[4:7], v[228:231], v[220:223], v[4:7]
	v_mfma_f32_16x16x32_bf16 v[0:3], v[236:239], v[220:223], v[0:3]
	v_mfma_f32_16x16x32_bf16 v[48:51], v[232:235], v[200:203], v[48:51]
	v_mfma_f32_16x16x32_bf16 v[40:43], v[240:243], v[200:203], v[40:43]
	v_mfma_f32_16x16x32_bf16 v[32:35], v[232:235], v[208:211], v[32:35]
	v_mfma_f32_16x16x32_bf16 v[24:27], v[240:243], v[208:211], v[24:27]
	v_mfma_f32_16x16x32_bf16 v[16:19], v[232:235], v[216:219], v[16:19]
	v_mfma_f32_16x16x32_bf16 v[8:11], v[240:243], v[216:219], v[8:11]
	v_mfma_f32_16x16x32_bf16 v[4:7], v[232:235], v[224:227], v[4:7]
	v_mfma_f32_16x16x32_bf16 v[0:3], v[240:243], v[224:227], v[0:3]
	s_add_i32 s44, s44, 2
	s_add_u32 s16, s16, 0x100
	s_addc_u32 s17, s17, 0
	s_add_u32 s42, s42, 0x100
	s_addc_u32 s43, s43, 0
	s_cmp_gt_u32 s44, 29
	s_barrier
	s_cbranch_scc0 .LBB0_125
	v_lshl_add_u32 v160, s39, 8, v142
	v_lshl_or_b32 v140, s38, 8, v144
	v_ashrrev_i32_e32 v141, 31, v140
	v_mov_b64_e32 v[138:139], s[2:3]
	v_cvt_pk_bf16_f32 v68, v68, v69
	v_cvt_pk_bf16_f32 v69, v70, v71
	v_cvt_pk_bf16_f32 v70, v64, v65
	v_add_u32_e32 v64, 0x80, v160
	v_mad_i64_i32 v[146:147], s[16:17], v160, s56, v[138:139]
	v_lshlrev_b64 v[140:141], 1, v[140:141]
	v_cvt_pk_bf16_f32 v112, v112, v113
	v_cvt_pk_bf16_f32 v113, v114, v115
	v_cvt_pk_bf16_f32 v114, v104, v105
	v_or_b32_e32 v104, 16, v160
	v_mad_i64_i32 v[64:65], s[16:17], v64, s56, v[138:139]
	v_cvt_pk_bf16_f32 v48, v48, v49
	v_cvt_pk_bf16_f32 v49, v50, v51
	v_cvt_pk_bf16_f32 v50, v40, v41
	v_add_u32_e32 v40, 0x90, v160
	v_lshl_add_u64 v[146:147], v[146:147], 0, v[140:141]
	v_mad_i64_i32 v[104:105], s[16:17], v104, s56, v[138:139]
	v_cvt_pk_bf16_f32 v96, v96, v97
	v_cvt_pk_bf16_f32 v97, v98, v99
	v_cvt_pk_bf16_f32 v98, v88, v89
	v_or_b32_e32 v88, 32, v160
	v_lshl_add_u64 v[64:65], v[64:65], 0, v[140:141]
	v_mad_i64_i32 v[40:41], s[16:17], v40, s56, v[138:139]
	v_cvt_pk_bf16_f32 v32, v32, v33
	v_cvt_pk_bf16_f32 v33, v34, v35
	v_cvt_pk_bf16_f32 v34, v24, v25
	v_add_u32_e32 v24, 0xa0, v160
	v_cvt_pk_bf16_f32 v115, v106, v107
	global_store_dwordx4 v[146:147], v[112:115], off offset:256
	v_mad_i64_i32 v[88:89], s[16:17], v88, s56, v[138:139]
	s_nop 0
	v_lshl_add_u64 v[112:113], v[104:105], 0, v[140:141]
	v_cvt_pk_bf16_f32 v80, v80, v81
	v_cvt_pk_bf16_f32 v81, v82, v83
	v_cvt_pk_bf16_f32 v82, v72, v73
	v_or_b32_e32 v72, 48, v160
	v_cvt_pk_bf16_f32 v51, v42, v43
	global_store_dwordx4 v[64:65], v[48:51], off offset:256
	v_mad_i64_i32 v[24:25], s[16:17], v24, s56, v[138:139]
	s_nop 0
	v_lshl_add_u64 v[48:49], v[40:41], 0, v[140:141]
	v_cvt_pk_bf16_f32 v16, v16, v17
	v_cvt_pk_bf16_f32 v17, v18, v19
	v_cvt_pk_bf16_f32 v18, v8, v9
	v_add_u32_e32 v8, 0xb0, v160
	v_cvt_pk_bf16_f32 v99, v90, v91
	global_store_dwordx4 v[112:113], v[96:99], off offset:256
	v_mad_i64_i32 v[72:73], s[16:17], v72, s56, v[138:139]
	s_nop 0
	v_lshl_add_u64 v[96:97], v[88:89], 0, v[140:141]
	v_cvt_pk_bf16_f32 v35, v26, v27
	global_store_dwordx4 v[48:49], v[32:35], off offset:256
	v_mad_i64_i32 v[8:9], s[16:17], v8, s56, v[138:139]
	s_nop 0
	v_lshl_add_u64 v[32:33], v[24:25], 0, v[140:141]
	v_cvt_pk_bf16_f32 v83, v74, v75
	global_store_dwordx4 v[96:97], v[80:83], off offset:256
	v_cvt_pk_bf16_f32 v19, v10, v11
	global_store_dwordx4 v[32:33], v[16:19], off offset:256
	s_and_b64 vcc, exec, s[0:1]
	v_lshl_add_u64 v[80:81], v[72:73], 0, v[140:141]
	v_lshl_add_u64 v[16:17], v[8:9], 0, v[140:141]
	s_mov_b32 s38, s4
	s_mov_b32 s39, s6
	s_mov_b64 s[20:21], s[14:15]
	s_mov_b64 s[16:17], s[12:13]
	v_cvt_pk_bf16_f32 v124, v124, v125
	v_cvt_pk_bf16_f32 v125, v126, v127
	v_cvt_pk_bf16_f32 v126, v120, v121
	v_cvt_pk_bf16_f32 v127, v122, v123
	global_store_dwordx4 v[146:147], v[124:127], off
	v_cvt_pk_bf16_f32 v104, v116, v117
	v_cvt_pk_bf16_f32 v105, v118, v119
	v_cvt_pk_bf16_f32 v106, v108, v109
	v_cvt_pk_bf16_f32 v107, v110, v111
	global_store_dwordx4 v[112:113], v[104:107], off
	v_cvt_pk_bf16_f32 v88, v100, v101
	v_cvt_pk_bf16_f32 v89, v102, v103
	v_cvt_pk_bf16_f32 v90, v92, v93
	v_cvt_pk_bf16_f32 v91, v94, v95
	global_store_dwordx4 v[96:97], v[88:91], off
	v_cvt_pk_bf16_f32 v72, v84, v85
	v_cvt_pk_bf16_f32 v73, v86, v87
	v_cvt_pk_bf16_f32 v74, v76, v77
	v_cvt_pk_bf16_f32 v75, v78, v79
	global_store_dwordx4 v[80:81], v[72:75], off
	v_cvt_pk_bf16_f32 v71, v66, v67
	global_store_dwordx4 v[80:81], v[68:71], off offset:256
	v_cvt_pk_bf16_f32 v60, v60, v61
	v_cvt_pk_bf16_f32 v61, v62, v63
	v_cvt_pk_bf16_f32 v62, v56, v57
	v_cvt_pk_bf16_f32 v63, v58, v59
	global_store_dwordx4 v[64:65], v[60:63], off
	v_cvt_pk_bf16_f32 v40, v52, v53
	v_cvt_pk_bf16_f32 v41, v54, v55
	v_cvt_pk_bf16_f32 v42, v44, v45
	v_cvt_pk_bf16_f32 v43, v46, v47
	global_store_dwordx4 v[48:49], v[40:43], off
	v_cvt_pk_bf16_f32 v24, v36, v37
	v_cvt_pk_bf16_f32 v25, v38, v39
	v_cvt_pk_bf16_f32 v26, v28, v29
	v_cvt_pk_bf16_f32 v27, v30, v31
	global_store_dwordx4 v[32:33], v[24:27], off
	v_cvt_pk_bf16_f32 v8, v20, v21
	v_cvt_pk_bf16_f32 v9, v22, v23
	v_cvt_pk_bf16_f32 v10, v12, v13
	v_cvt_pk_bf16_f32 v11, v14, v15
	global_store_dwordx4 v[16:17], v[8:11], off
	v_cvt_pk_bf16_f32 v4, v4, v5
	v_cvt_pk_bf16_f32 v5, v6, v7
	v_cvt_pk_bf16_f32 v6, v0, v1
	v_cvt_pk_bf16_f32 v7, v2, v3
	global_store_dwordx4 v[16:17], v[4:7], off offset:256
	s_cbranch_vccz .LBB0_118
	s_waitcnt vmcnt(0)
	s_cmpk_gt_u32 s24, 0xff
	s_cbranch_scc1 .LBB0_129
	s_barrier

; #define PG8_STAGE(bufoff, gbase, voff) do { _Pragma("unroll") for (int _i = 0; _i < 2; ++_i) \
;         __builtin_amdgcn_global_load_lds((const unsigned*)((const char*)(gbase) + (voff)[_i]), (LAS unsigned*)(lds + (bufoff) + ldsw + _i * 8192), 16, 0, 0); } while (0)
; #define PG8_LDA(dst, b, h) do { _Pragma("unroll") for (int m = 0; m < 4; ++m) _Pragma("unroll") for (int k = 0; k < 2; ++k) dst[m][k] = *(const LAS bf16x8*)(lds + PG8_SA(b, h) + aoff + m * 2048 + k * 1024); } while (0)
; #define PG8_LDB(dst, b, h) do { _Pragma("unroll") for (int n = 0; n < 2; ++n) _Pragma("unroll") for (int k = 0; k < 2; ++k) dst[n][k] = *(const LAS bf16x8*)(lds + PG8_SB(b, h) + boff + n * 2048 + k * 1024); } while (0)
; #define PG8_MMA(ai, bj, At, Bt) do { __builtin_amdgcn_s_setprio(1); _Pragma("unroll") for (int m = 0; m < 4; ++m) _Pragma("unroll") for (int n = 0; n < 2; ++n) _Pragma("unroll") for (int k = 0; k < 2; ++k) \
;         acc[ai][bj][m][n] = __builtin_amdgcn_mfma_f32_16x16x32_bf16(Bt[n][k], At[m][k], acc[ai][bj][m][n], 0, 0, 0); __builtin_amdgcn_s_setprio(0); } while (0)
; #define PG8_WAIT_V(n) asm volatile("s_waitcnt vmcnt(" #n ")" ::: "memory")
; #define PG8_WAIT_L(n) asm volatile("s_waitcnt lgkmcnt(" #n ")" ::: "memory")
; template <class Epi, class Sched>
; __device__ __forceinline__ void gemm_phase(LAS unsigned char* lds, const Gemm g, const Sched& S, const Epi& E) {
;     ...
;         for (int t = 0; t < nt; t += 2) {
;             const bool last = (t == nt - 2);
;             const char* a1 = cA + (size_t)(t + 1) * kstep;
;             const char* a2 = last ? nA : cA + (size_t)(t + 2) * kstep; const char* b2 = last ? nB : cB + (size_t)(t + 2) * kstep;
;             const char* a3 = a2 + kstep; const char* b3 = b2 + kstep;
;             PG8_LDB(B0, 0, 0); PG8_SCHED; PG8_LDA(At, 0, 0); PG8_STAGE(PG8_SA(1, 1), a1 + hstep, voffA);
;             PG8_WAIT_L(8); PG8_BAR; PG8_WAIT_L(0); PG8_MMA(0, 0, At, B0); PG8_BAR; PG8_SCHED;
;             PG8_LDB(B1, 0, 1); PG8_STAGE(PG8_SB(0, 0), b2, voffB);
;             PG8_BAR; PG8_WAIT_L(0); PG8_MMA(0, 1, At, B1); PG8_BAR;
;             PG8_LDA(At, 0, 1); PG8_STAGE(PG8_SA(0, 0), a2, voffA);
;             PG8_BAR; PG8_WAIT_L(0); PG8_MMA(1, 0, At, B0); PG8_BAR; PG8_SCHED;
;             PG8_STAGE(PG8_SB(0, 1), b2 + hstep, voffB);
;             PG8_WAIT_V(6); PG8_BAR; PG8_MMA(1, 1, At, B1); PG8_BAR;
.LBB0_170:
	s_add_i32 s53, s22, 2
	s_add_u32 s20, s16, 0x100
	s_addc_u32 s21, s17, 0
	s_add_i32 s54, 0, 0x10000
	ds_read_b128 v[128:131], v141
	ds_read_b128 v[132:135], v141 offset:1024
	ds_read_b128 v[136:139], v141 offset:2048
	ds_read_b128 v[160:163], v141 offset:3072
	s_cmp_eq_u32 s15, s22
	s_cselect_b32 s22, s4, s51
	s_cselect_b32 s25, s7, s21
	s_cselect_b32 s24, s6, s20
	s_cselect_b32 s23, s5, s52
	s_add_i32 m0, s35, 0xc000
	ds_read_b128 v[164:167], v173
	ds_read_b128 v[174:177], v173 offset:1024
	ds_read_b128 v[200:203], v173 offset:2048
	ds_read_b128 v[204:207], v173 offset:3072
	ds_read_b128 v[208:211], v173 offset:4096
	ds_read_b128 v[212:215], v173 offset:5120
	ds_read_b128 v[216:219], v173 offset:6144
	ds_read_b128 v[220:223], v173 offset:7168
	global_load_lds_dwordx4 v142, s[16:17]
	s_add_i32 m0, s35, 0xe000
	s_nop 0
	global_load_lds_dwordx4 v144, s[16:17]
	s_waitcnt lgkmcnt(8)
	s_barrier
	s_waitcnt lgkmcnt(0)
	v_mfma_f32_16x16x32_bf16 v[124:127], v[128:131], v[164:167], v[124:127]
	v_mfma_f32_16x16x32_bf16 v[120:123], v[136:139], v[164:167], v[120:123]
	v_mfma_f32_16x16x32_bf16 v[116:119], v[128:131], v[200:203], v[116:119]
	v_mfma_f32_16x16x32_bf16 v[112:115], v[136:139], v[200:203], v[112:115]
	v_mfma_f32_16x16x32_bf16 v[100:103], v[128:131], v[208:211], v[100:103]
	v_mfma_f32_16x16x32_bf16 v[96:99], v[136:139], v[208:211], v[96:99]
	v_mfma_f32_16x16x32_bf16 v[84:87], v[128:131], v[216:219], v[84:87]
	v_mfma_f32_16x16x32_bf16 v[80:83], v[136:139], v[216:219], v[80:83]
	v_mfma_f32_16x16x32_bf16 v[124:127], v[132:135], v[174:177], v[124:127]
	v_mfma_f32_16x16x32_bf16 v[120:123], v[160:163], v[174:177], v[120:123]
	v_mfma_f32_16x16x32_bf16 v[116:119], v[132:135], v[204:207], v[116:119]
	v_mfma_f32_16x16x32_bf16 v[112:115], v[160:163], v[204:207], v[112:115]
	v_mfma_f32_16x16x32_bf16 v[100:103], v[132:135], v[212:215], v[100:103]
	v_mfma_f32_16x16x32_bf16 v[96:99], v[160:163], v[212:215], v[96:99]
	v_mfma_f32_16x16x32_bf16 v[84:87], v[132:135], v[220:223], v[84:87]
	v_mfma_f32_16x16x32_bf16 v[80:83], v[160:163], v[220:223], v[80:83]
	s_barrier
	s_add_i32 s55, 0, 0x14000
	s_add_i32 s16, s54, s29
	ds_read_b128 v[224:227], v141 offset:16384
	ds_read_b128 v[228:231], v141 offset:17408
	ds_read_b128 v[232:235], v141 offset:18432
	ds_read_b128 v[236:239], v141 offset:19456
	s_add_u32 s84, s22, 0x80
	s_addc_u32 s85, s23, 0
	s_mov_b32 m0, s16
	s_nop 0
	global_load_lds_dwordx4 v148, s[22:23]
	s_add_i32 m0, s16, 0x2000
	s_nop 0
	global_load_lds_dwordx4 v140, s[22:23]
	s_waitcnt lgkmcnt(0)
	s_barrier
	v_mfma_f32_16x16x32_bf16 v[108:111], v[224:227], v[164:167], v[108:111]
	v_mfma_f32_16x16x32_bf16 v[104:107], v[232:235], v[164:167], v[104:107]
	v_mfma_f32_16x16x32_bf16 v[92:95], v[224:227], v[200:203], v[92:95]
	v_mfma_f32_16x16x32_bf16 v[88:91], v[232:235], v[200:203], v[88:91]
	v_mfma_f32_16x16x32_bf16 v[76:79], v[224:227], v[208:211], v[76:79]
	v_mfma_f32_16x16x32_bf16 v[72:75], v[232:235], v[208:211], v[72:75]
	v_mfma_f32_16x16x32_bf16 v[68:71], v[224:227], v[216:219], v[68:71]
	v_mfma_f32_16x16x32_bf16 v[64:67], v[232:235], v[216:219], v[64:67]
	v_mfma_f32_16x16x32_bf16 v[108:111], v[228:231], v[174:177], v[108:111]
	v_mfma_f32_16x16x32_bf16 v[104:107], v[236:239], v[174:177], v[104:107]
	v_mfma_f32_16x16x32_bf16 v[92:95], v[228:231], v[204:207], v[92:95]
	v_mfma_f32_16x16x32_bf16 v[88:91], v[236:239], v[204:207], v[88:91]
	v_mfma_f32_16x16x32_bf16 v[76:79], v[228:231], v[212:215], v[76:79]
	v_mfma_f32_16x16x32_bf16 v[72:75], v[236:239], v[212:215], v[72:75]
	v_mfma_f32_16x16x32_bf16 v[68:71], v[228:231], v[220:223], v[68:71]
	v_mfma_f32_16x16x32_bf16 v[64:67], v[236:239], v[220:223], v[64:67]
	s_mov_b32 m0, s35
	s_add_u32 s86, s24, 0x80
	s_addc_u32 s87, s25, 0
	s_barrier
	ds_read_b128 v[164:167], v173 offset:16384
	ds_read_b128 v[174:177], v173 offset:17408
	ds_read_b128 v[200:203], v173 offset:18432
	ds_read_b128 v[204:207], v173 offset:19456
	ds_read_b128 v[208:211], v173 offset:20480
	ds_read_b128 v[212:215], v173 offset:21504
	ds_read_b128 v[216:219], v173 offset:22528
	ds_read_b128 v[220:223], v173 offset:23552
	global_load_lds_dwordx4 v148, s[24:25]
	s_mov_b32 m0, s36
	s_nop 0
	global_load_lds_dwordx4 v140, s[24:25]
	s_waitcnt lgkmcnt(0)
	s_barrier
	v_mfma_f32_16x16x32_bf16 v[60:63], v[128:131], v[164:167], v[60:63]
	v_mfma_f32_16x16x32_bf16 v[56:59], v[136:139], v[164:167], v[56:59]
	v_mfma_f32_16x16x32_bf16 v[52:55], v[128:131], v[200:203], v[52:55]
	v_mfma_f32_16x16x32_bf16 v[48:51], v[136:139], v[200:203], v[48:51]
	v_mfma_f32_16x16x32_bf16 v[36:39], v[128:131], v[208:211], v[36:39]
	v_mfma_f32_16x16x32_bf16 v[32:35], v[136:139], v[208:211], v[32:35]
	v_mfma_f32_16x16x32_bf16 v[20:23], v[128:131], v[216:219], v[20:23]
	v_mfma_f32_16x16x32_bf16 v[16:19], v[136:139], v[216:219], v[16:19]
	v_mfma_f32_16x16x32_bf16 v[60:63], v[132:135], v[174:177], v[60:63]
	v_mfma_f32_16x16x32_bf16 v[56:59], v[160:163], v[174:177], v[56:59]
	v_mfma_f32_16x16x32_bf16 v[52:55], v[132:135], v[204:207], v[52:55]
	v_mfma_f32_16x16x32_bf16 v[48:51], v[160:163], v[204:207], v[48:51]
	v_mfma_f32_16x16x32_bf16 v[36:39], v[132:135], v[212:215], v[36:39]
	v_mfma_f32_16x16x32_bf16 v[32:35], v[160:163], v[212:215], v[32:35]
	v_mfma_f32_16x16x32_bf16 v[20:23], v[132:135], v[220:223], v[20:23]
	v_mfma_f32_16x16x32_bf16 v[16:19], v[160:163], v[220:223], v[16:19]
	s_barrier
	s_add_u32 s16, s22, 0x160000
	s_addc_u32 s17, s23, 0
	s_add_i32 s54, s55, s29
	s_mov_b32 m0, s54
	s_nop 0
	global_load_lds_dwordx4 v148, s[16:17]
	s_add_i32 m0, s54, 0x2000
	s_nop 0
	global_load_lds_dwordx4 v140, s[16:17]
	s_waitcnt vmcnt(6)
	s_barrier
; #define PG8_STAGE(bufoff, gbase, voff) do { _Pragma("unroll") for (int _i = 0; _i < 2; ++_i) \
;         __builtin_amdgcn_global_load_lds((const unsigned*)((const char*)(gbase) + (voff)[_i]), (LAS unsigned*)(lds + (bufoff) + ldsw + _i * 8192), 16, 0, 0); } while (0)
; #define PG8_LDA(dst, b, h) do { _Pragma("unroll") for (int m = 0; m < 4; ++m) _Pragma("unroll") for (int k = 0; k < 2; ++k) dst[m][k] = *(const LAS bf16x8*)(lds + PG8_SA(b, h) + aoff + m * 2048 + k * 1024); } while (0)
; #define PG8_LDB(dst, b, h) do { _Pragma("unroll") for (int n = 0; n < 2; ++n) _Pragma("unroll") for (int k = 0; k < 2; ++k) dst[n][k] = *(const LAS bf16x8*)(lds + PG8_SB(b, h) + boff + n * 2048 + k * 1024); } while (0)
; #define PG8_MMA(ai, bj, At, Bt) do { __builtin_amdgcn_s_setprio(1); _Pragma("unroll") for (int m = 0; m < 4; ++m) _Pragma("unroll") for (int n = 0; n < 2; ++n) _Pragma("unroll") for (int k = 0; k < 2; ++k) \
;         acc[ai][bj][m][n] = __builtin_amdgcn_mfma_f32_16x16x32_bf16(Bt[n][k], At[m][k], acc[ai][bj][m][n], 0, 0, 0); __builtin_amdgcn_s_setprio(0); } while (0)
; #define PG8_WAIT_V(n) asm volatile("s_waitcnt vmcnt(" #n ")" ::: "memory")
; #define PG8_WAIT_L(n) asm volatile("s_waitcnt lgkmcnt(" #n ")" ::: "memory")
; #define PG8_BAR __builtin_amdgcn_s_barrier()
; #define PG8_SCHED __builtin_amdgcn_sched_barrier(0)
; template <class Epi, class Sched>
; __device__ __forceinline__ void gemm_phase(LAS unsigned char* lds, const Gemm g, const Sched& S, const Epi& E) {
;     ...
;             PG8_WAIT_V(6); PG8_BAR; PG8_MMA(1, 1, At, B1); PG8_BAR;
;             PG8_LDB(B0, 1, 0); PG8_SCHED; PG8_LDA(At, 1, 0); PG8_STAGE(PG8_SA(0, 1), a2 + hstep, voffA);
;             PG8_WAIT_L(8); PG8_BAR; PG8_WAIT_L(0); PG8_MMA(0, 0, At, B0); PG8_BAR; PG8_SCHED;
;             PG8_LDB(B1, 1, 1); PG8_STAGE(PG8_SB(1, 0), b3, voffB);
;             PG8_BAR; PG8_WAIT_L(0); PG8_MMA(0, 1, At, B1); PG8_BAR;
;             PG8_LDA(At, 1, 1); PG8_STAGE(PG8_SA(1, 0), a3, voffA);
;             PG8_BAR; PG8_WAIT_L(0); PG8_MMA(1, 0, At, B0); PG8_BAR; PG8_SCHED;
	v_mfma_f32_16x16x32_bf16 v[44:47], v[224:227], v[164:167], v[44:47]
	v_mfma_f32_16x16x32_bf16 v[40:43], v[232:235], v[164:167], v[40:43]
	v_mfma_f32_16x16x32_bf16 v[28:31], v[224:227], v[200:203], v[28:31]
	v_mfma_f32_16x16x32_bf16 v[24:27], v[232:235], v[200:203], v[24:27]
	v_mfma_f32_16x16x32_bf16 v[12:15], v[224:227], v[208:211], v[12:15]
	v_mfma_f32_16x16x32_bf16 v[8:11], v[232:235], v[208:211], v[8:11]
	v_mfma_f32_16x16x32_bf16 v[4:7], v[224:227], v[216:219], v[4:7]
	v_mfma_f32_16x16x32_bf16 v[0:3], v[232:235], v[216:219], v[0:3]
	v_mfma_f32_16x16x32_bf16 v[44:47], v[228:231], v[174:177], v[44:47]
	v_mfma_f32_16x16x32_bf16 v[40:43], v[236:239], v[174:177], v[40:43]
	v_mfma_f32_16x16x32_bf16 v[28:31], v[228:231], v[204:207], v[28:31]
	v_mfma_f32_16x16x32_bf16 v[24:27], v[236:239], v[204:207], v[24:27]
	v_mfma_f32_16x16x32_bf16 v[12:15], v[228:231], v[212:215], v[12:15]
	v_mfma_f32_16x16x32_bf16 v[8:11], v[236:239], v[212:215], v[8:11]
	v_mfma_f32_16x16x32_bf16 v[4:7], v[228:231], v[220:223], v[4:7]
	v_mfma_f32_16x16x32_bf16 v[0:3], v[236:239], v[220:223], v[0:3]
	s_add_i32 s54, 0, 0x18000
	s_barrier
	ds_read_b128 v[128:131], v141 offset:32768
	ds_read_b128 v[132:135], v141 offset:33792
	ds_read_b128 v[136:139], v141 offset:34816
	ds_read_b128 v[160:163], v141 offset:35840
	s_add_u32 s16, s24, 0x160000
	s_addc_u32 s17, s25, 0
	s_mov_b32 m0, s37
	ds_read_b128 v[164:167], v173 offset:32768
	ds_read_b128 v[174:177], v173 offset:33792
	ds_read_b128 v[200:203], v173 offset:34816
	ds_read_b128 v[204:207], v173 offset:35840
	ds_read_b128 v[208:211], v173 offset:36864
	ds_read_b128 v[212:215], v173 offset:37888
	ds_read_b128 v[216:219], v173 offset:38912
	ds_read_b128 v[220:223], v173 offset:39936
	global_load_lds_dwordx4 v148, s[16:17]
	s_mov_b32 m0, s38
	s_nop 0
	global_load_lds_dwordx4 v140, s[16:17]
	s_waitcnt lgkmcnt(8)
	s_barrier
	s_waitcnt lgkmcnt(0)
	v_mfma_f32_16x16x32_bf16 v[124:127], v[128:131], v[164:167], v[124:127]
	v_mfma_f32_16x16x32_bf16 v[120:123], v[136:139], v[164:167], v[120:123]
	v_mfma_f32_16x16x32_bf16 v[116:119], v[128:131], v[200:203], v[116:119]
	v_mfma_f32_16x16x32_bf16 v[112:115], v[136:139], v[200:203], v[112:115]
	v_mfma_f32_16x16x32_bf16 v[100:103], v[128:131], v[208:211], v[100:103]
	v_mfma_f32_16x16x32_bf16 v[96:99], v[136:139], v[208:211], v[96:99]
	v_mfma_f32_16x16x32_bf16 v[84:87], v[128:131], v[216:219], v[84:87]
	v_mfma_f32_16x16x32_bf16 v[80:83], v[136:139], v[216:219], v[80:83]
	v_mfma_f32_16x16x32_bf16 v[124:127], v[132:135], v[174:177], v[124:127]
	v_mfma_f32_16x16x32_bf16 v[120:123], v[160:163], v[174:177], v[120:123]
	v_mfma_f32_16x16x32_bf16 v[116:119], v[132:135], v[204:207], v[116:119]
	v_mfma_f32_16x16x32_bf16 v[112:115], v[160:163], v[204:207], v[112:115]
	v_mfma_f32_16x16x32_bf16 v[100:103], v[132:135], v[212:215], v[100:103]
	v_mfma_f32_16x16x32_bf16 v[96:99], v[160:163], v[212:215], v[96:99]
	v_mfma_f32_16x16x32_bf16 v[84:87], v[132:135], v[220:223], v[84:87]
	v_mfma_f32_16x16x32_bf16 v[80:83], v[160:163], v[220:223], v[80:83]
	s_barrier
	s_add_i32 s24, 0, 0x1c000
	s_add_i32 s16, s54, s29
	s_mov_b32 m0, s16
	ds_read_b128 v[224:227], v141 offset:49152
	ds_read_b128 v[228:231], v141 offset:50176
	ds_read_b128 v[232:235], v141 offset:51200
	ds_read_b128 v[236:239], v141 offset:52224
	global_load_lds_dwordx4 v148, s[84:85]
	s_add_i32 m0, s16, 0x2000
	s_nop 0
	global_load_lds_dwordx4 v140, s[84:85]
	s_waitcnt lgkmcnt(0)
	s_barrier
	v_mfma_f32_16x16x32_bf16 v[108:111], v[224:227], v[164:167], v[108:111]
	v_mfma_f32_16x16x32_bf16 v[104:107], v[232:235], v[164:167], v[104:107]
	v_mfma_f32_16x16x32_bf16 v[92:95], v[224:227], v[200:203], v[92:95]
	v_mfma_f32_16x16x32_bf16 v[88:91], v[232:235], v[200:203], v[88:91]
	v_mfma_f32_16x16x32_bf16 v[76:79], v[224:227], v[208:211], v[76:79]
	v_mfma_f32_16x16x32_bf16 v[72:75], v[232:235], v[208:211], v[72:75]
	v_mfma_f32_16x16x32_bf16 v[68:71], v[224:227], v[216:219], v[68:71]
	v_mfma_f32_16x16x32_bf16 v[64:67], v[232:235], v[216:219], v[64:67]
	v_mfma_f32_16x16x32_bf16 v[108:111], v[228:231], v[174:177], v[108:111]
	v_mfma_f32_16x16x32_bf16 v[104:107], v[236:239], v[174:177], v[104:107]
	v_mfma_f32_16x16x32_bf16 v[92:95], v[228:231], v[204:207], v[92:95]
	v_mfma_f32_16x16x32_bf16 v[88:91], v[236:239], v[204:207], v[88:91]
	v_mfma_f32_16x16x32_bf16 v[76:79], v[228:231], v[212:215], v[76:79]
	v_mfma_f32_16x16x32_bf16 v[72:75], v[236:239], v[212:215], v[72:75]
	v_mfma_f32_16x16x32_bf16 v[68:71], v[228:231], v[220:223], v[68:71]
	v_mfma_f32_16x16x32_bf16 v[64:67], v[236:239], v[220:223], v[64:67]
	s_mov_b32 m0, s41
	s_barrier
	ds_read_b128 v[164:167], v173 offset:49152
	ds_read_b128 v[174:177], v173 offset:50176
	ds_read_b128 v[200:203], v173 offset:51200
	ds_read_b128 v[204:207], v173 offset:52224
	ds_read_b128 v[208:211], v173 offset:53248
	ds_read_b128 v[212:215], v173 offset:54272
	ds_read_b128 v[216:219], v173 offset:55296
	ds_read_b128 v[220:223], v173 offset:56320
	global_load_lds_dwordx4 v148, s[86:87]
	s_mov_b32 m0, s42
	s_nop 0
	global_load_lds_dwordx4 v140, s[86:87]
	s_waitcnt lgkmcnt(0)
	s_barrier
	v_mfma_f32_16x16x32_bf16 v[60:63], v[128:131], v[164:167], v[60:63]
	v_mfma_f32_16x16x32_bf16 v[56:59], v[136:139], v[164:167], v[56:59]
	v_mfma_f32_16x16x32_bf16 v[52:55], v[128:131], v[200:203], v[52:55]
	v_mfma_f32_16x16x32_bf16 v[48:51], v[136:139], v[200:203], v[48:51]
	v_mfma_f32_16x16x32_bf16 v[36:39], v[128:131], v[208:211], v[36:39]
	v_mfma_f32_16x16x32_bf16 v[32:35], v[136:139], v[208:211], v[32:35]
	v_mfma_f32_16x16x32_bf16 v[20:23], v[128:131], v[216:219], v[20:23]
	v_mfma_f32_16x16x32_bf16 v[16:19], v[136:139], v[216:219], v[16:19]
	v_mfma_f32_16x16x32_bf16 v[60:63], v[132:135], v[174:177], v[60:63]
	v_mfma_f32_16x16x32_bf16 v[56:59], v[160:163], v[174:177], v[56:59]
	v_mfma_f32_16x16x32_bf16 v[52:55], v[132:135], v[204:207], v[52:55]
	v_mfma_f32_16x16x32_bf16 v[48:51], v[160:163], v[204:207], v[48:51]
	v_mfma_f32_16x16x32_bf16 v[36:39], v[132:135], v[212:215], v[36:39]
	v_mfma_f32_16x16x32_bf16 v[32:35], v[160:163], v[212:215], v[32:35]
	v_mfma_f32_16x16x32_bf16 v[20:23], v[132:135], v[220:223], v[20:23]
	v_mfma_f32_16x16x32_bf16 v[16:19], v[160:163], v[220:223], v[16:19]
	s_barrier
; #define PG8_STAGE(bufoff, gbase, voff) do { _Pragma("unroll") for (int _i = 0; _i < 2; ++_i) \
;         __builtin_amdgcn_global_load_lds((const unsigned*)((const char*)(gbase) + (voff)[_i]), (LAS unsigned*)(lds + (bufoff) + ldsw + _i * 8192), 16, 0, 0); } while (0)
; #define PG8_MMA(ai, bj, At, Bt) do { __builtin_amdgcn_s_setprio(1); _Pragma("unroll") for (int m = 0; m < 4; ++m) _Pragma("unroll") for (int n = 0; n < 2; ++n) _Pragma("unroll") for (int k = 0; k < 2; ++k) \
;         acc[ai][bj][m][n] = __builtin_amdgcn_mfma_f32_16x16x32_bf16(Bt[n][k], At[m][k], acc[ai][bj][m][n], 0, 0, 0); __builtin_amdgcn_s_setprio(0); } while (0)
; #define PG8_WAIT_V(n) asm volatile("s_waitcnt vmcnt(" #n ")" ::: "memory")
; #define PG8_BAR __builtin_amdgcn_s_barrier()
;     __device__ __forceinline__ void operator()(const f32x4 (&acc)[2][2][4][2], const Unit& u, int wr, int wc, int fr, int fq) const {
;     ...
;         const float* base = (u.pm < 32) ? base_lo : base_hi;
; #pragma unroll
;         for (int ai = 0; ai < 2; ++ai) {
;             f32x4 bs[4][2][2];
; #pragma unroll
;             for (int m = 0; m < 4; ++m) { const size_t off = (size_t)(row0 + ai * HALF + m * 16) * DM + col0;
; #pragma unroll
;                 for (int bj = 0; bj < 2; ++bj)
; #pragma unroll
;                     for (int n = 0; n < 2; ++n) bs[m][bj][n] = *(const f32x4*)(base + off + bj * HALF + n * 16); }
; #pragma unroll
;             for (int m = 0; m < 4; ++m) { const size_t off = (size_t)(row0 + ai * HALF + m * 16) * DM + col0;
; #pragma unroll
;                 for (int bj = 0; bj < 2; ++bj)
; #pragma unroll
;                     for (int n = 0; n < 2; ++n) *(f32x4*)(out + off + bj * HALF + n * 16) = bs[m][bj][n] + scale * acc[ai][bj][m][n]; }
;             asm volatile("" ::: "memory");
; template <class Epi, class Sched>
; __device__ __forceinline__ void gemm_phase(LAS unsigned char* lds, const Gemm g, const Sched& S, const Epi& E) {
;     ...
;             PG8_STAGE(PG8_SB(1, 1), b3 + hstep, voffB);
;             PG8_WAIT_V(6); PG8_BAR; PG8_MMA(1, 1, At, B1); PG8_BAR;
	s_add_u32 s16, s22, 0x160080
	s_addc_u32 s17, s23, 0
	s_add_i32 s22, s24, s29
	s_mov_b32 m0, s22
	s_nop 0
	global_load_lds_dwordx4 v148, s[16:17]
	s_add_i32 m0, s22, 0x2000
	s_nop 0
	global_load_lds_dwordx4 v140, s[16:17]
	s_waitcnt vmcnt(6)
	s_barrier
	v_mfma_f32_16x16x32_bf16 v[44:47], v[224:227], v[164:167], v[44:47]
	v_mfma_f32_16x16x32_bf16 v[40:43], v[232:235], v[164:167], v[40:43]
	v_mfma_f32_16x16x32_bf16 v[28:31], v[224:227], v[200:203], v[28:31]
	v_mfma_f32_16x16x32_bf16 v[24:27], v[232:235], v[200:203], v[24:27]
	v_mfma_f32_16x16x32_bf16 v[12:15], v[224:227], v[208:211], v[12:15]
	v_mfma_f32_16x16x32_bf16 v[8:11], v[232:235], v[208:211], v[8:11]
	v_mfma_f32_16x16x32_bf16 v[4:7], v[224:227], v[216:219], v[4:7]
	v_mfma_f32_16x16x32_bf16 v[0:3], v[232:235], v[216:219], v[0:3]
	v_mfma_f32_16x16x32_bf16 v[44:47], v[228:231], v[174:177], v[44:47]
	v_mfma_f32_16x16x32_bf16 v[40:43], v[236:239], v[174:177], v[40:43]
	v_mfma_f32_16x16x32_bf16 v[28:31], v[228:231], v[204:207], v[28:31]
	v_mfma_f32_16x16x32_bf16 v[24:27], v[236:239], v[204:207], v[24:27]
	v_mfma_f32_16x16x32_bf16 v[12:15], v[228:231], v[212:215], v[12:15]
	v_mfma_f32_16x16x32_bf16 v[8:11], v[236:239], v[212:215], v[8:11]
	v_mfma_f32_16x16x32_bf16 v[4:7], v[228:231], v[220:223], v[4:7]
	v_mfma_f32_16x16x32_bf16 v[0:3], v[236:239], v[220:223], v[0:3]
	s_add_u32 s51, s51, 0x100
	s_addc_u32 s52, s52, 0
	s_cmp_ge_i32 s53, s50
	s_mov_b64 s[16:17], s[20:21]
	s_mov_b32 s22, s53
	s_barrier
	s_cbranch_scc0 .LBB0_170
	v_lshl_add_u32 v146, s48, 8, v170
	v_lshl_or_b32 v160, s49, 8, v172
	s_mov_b64 s[16:17], -1
	s_cmp_lt_i32 s82, 0
	v_ashrrev_i32_e32 v161, 31, v160
	v_ashrrev_i32_e32 v147, 31, v146
	s_cbranch_scc0 .LBB0_173
	s_cmp_lt_i32 s48, 32
	s_cselect_b32 s17, s13, s61
	s_cselect_b32 s16, s12, s60
	v_lshlrev_b64 v[162:163], 2, v[160:161]
	v_lshl_add_u64 v[164:165], s[16:17], 0, v[162:163]
	v_lshlrev_b64 v[166:167], 13, v[146:147]
	v_lshl_add_u64 v[128:129], v[164:165], 0, v[166:167]
	global_load_dwordx4 v[174:177], v[128:129], off
	global_load_dwordx4 v[200:203], v[128:129], off offset:64
	global_load_dwordx4 v[204:207], v[128:129], off offset:512
	global_load_dwordx4 v[208:211], v[128:129], off offset:576
	v_or_b32_e32 v128, 16, v146
	v_ashrrev_i32_e32 v129, 31, v128
	v_lshlrev_b64 v[248:249], 13, v[128:129]
	v_lshl_add_u64 v[128:129], v[164:165], 0, v[248:249]
	global_load_dwordx4 v[212:215], v[128:129], off
	global_load_dwordx4 v[216:219], v[128:129], off offset:64
	global_load_dwordx4 v[220:223], v[128:129], off offset:512
	global_load_dwordx4 v[224:227], v[128:129], off offset:576
	v_or_b32_e32 v128, 32, v146
	v_ashrrev_i32_e32 v129, 31, v128
	v_lshlrev_b64 v[188:189], 13, v[128:129]
	v_lshl_add_u64 v[128:129], v[164:165], 0, v[188:189]
	global_load_dwordx4 v[228:231], v[128:129], off
	global_load_dwordx4 v[232:235], v[128:129], off offset:64
	global_load_dwordx4 v[236:239], v[128:129], off offset:512
	global_load_dwordx4 v[240:243], v[128:129], off offset:576
	v_or_b32_e32 v128, 48, v146
	v_ashrrev_i32_e32 v129, 31, v128
	v_lshlrev_b64 v[168:169], 13, v[128:129]
	v_lshl_add_u64 v[128:129], v[164:165], 0, v[168:169]
	global_load_dwordx4 v[244:247], v[128:129], off
	global_load_dwordx4 v[136:139], v[128:129], off offset:64
	global_load_dwordx4 v[132:135], v[128:129], off offset:512
	s_nop 0
	global_load_dwordx4 v[128:131], v[128:129], off offset:576
	v_lshl_add_u64 v[190:191], s[60:61], 0, v[166:167]
	v_lshl_add_u64 v[190:191], v[190:191], 0, v[162:163]
	v_lshl_add_u64 v[188:189], s[60:61], 0, v[188:189]
	v_lshl_add_u64 v[188:189], v[188:189], 0, v[162:163]
	v_lshl_add_u64 v[168:169], s[60:61], 0, v[168:169]
	v_lshl_add_u64 v[168:169], v[168:169], 0, v[162:163]
	s_mov_b64 s[16:17], 0x100000
	s_waitcnt vmcnt(0)
	v_pk_fma_f32 v[176:177], v[126:127], 0.5, v[176:177] op_sel_hi:[1,0,1]
	v_pk_fma_f32 v[174:175], v[124:125], 0.5, v[174:175] op_sel_hi:[1,0,1]
	global_store_dwordx4 v[190:191], v[174:177], off
	v_pk_fma_f32 v[138:139], v[82:83], 0.5, v[138:139] op_sel_hi:[1,0,1]
	s_nop 0
	v_pk_fma_f32 v[176:177], v[122:123], 0.5, v[202:203] op_sel_hi:[1,0,1]
	v_pk_fma_f32 v[174:175], v[120:121], 0.5, v[200:201] op_sel_hi:[1,0,1]
	global_store_dwordx4 v[190:191], v[174:177], off offset:64
	v_pk_fma_f32 v[136:137], v[80:81], 0.5, v[136:137] op_sel_hi:[1,0,1]
	v_pk_fma_f32 v[134:135], v[70:71], 0.5, v[134:135] op_sel_hi:[1,0,1]
	v_pk_fma_f32 v[176:177], v[110:111], 0.5, v[206:207] op_sel_hi:[1,0,1]
	v_pk_fma_f32 v[174:175], v[108:109], 0.5, v[204:205] op_sel_hi:[1,0,1]
	global_store_dwordx4 v[190:191], v[174:177], off offset:512
	v_pk_fma_f32 v[132:133], v[68:69], 0.5, v[132:133] op_sel_hi:[1,0,1]
	v_pk_fma_f32 v[130:131], v[66:67], 0.5, v[130:131] op_sel_hi:[1,0,1]
	v_pk_fma_f32 v[176:177], v[106:107], 0.5, v[210:211] op_sel_hi:[1,0,1]
	v_pk_fma_f32 v[174:175], v[104:105], 0.5, v[208:209] op_sel_hi:[1,0,1]
	global_store_dwordx4 v[190:191], v[174:177], off offset:576
	v_lshl_add_u64 v[190:191], s[60:61], 0, v[248:249]
	v_lshl_add_u64 v[190:191], v[190:191], 0, v[162:163]
	v_pk_fma_f32 v[176:177], v[118:119], 0.5, v[214:215] op_sel_hi:[1,0,1]
	v_pk_fma_f32 v[174:175], v[116:117], 0.5, v[212:213] op_sel_hi:[1,0,1]
	global_store_dwordx4 v[190:191], v[174:177], off
	v_pk_fma_f32 v[128:129], v[64:65], 0.5, v[128:129] op_sel_hi:[1,0,1]
	global_store_dwordx4 v[168:169], v[136:139], off offset:64
	v_pk_fma_f32 v[176:177], v[114:115], 0.5, v[218:219] op_sel_hi:[1,0,1]
	v_pk_fma_f32 v[174:175], v[112:113], 0.5, v[216:217] op_sel_hi:[1,0,1]
	global_store_dwordx4 v[190:191], v[174:177], off offset:64
	global_store_dwordx4 v[168:169], v[132:135], off offset:512
	global_store_dwordx4 v[168:169], v[128:131], off offset:576
;     __device__ __forceinline__ void operator()(const f32x4 (&acc)[2][2][4][2], const Unit& u, int wr, int wc, int fr, int fq) const {
;     ...
;         for (int ai = 0; ai < 2; ++ai) {
;             f32x4 bs[4][2][2];
; #pragma unroll
;             for (int m = 0; m < 4; ++m) { const size_t off = (size_t)(row0 + ai * HALF + m * 16) * DM + col0;
; #pragma unroll
;                 for (int bj = 0; bj < 2; ++bj)
; #pragma unroll
;                     for (int n = 0; n < 2; ++n) bs[m][bj][n] = *(const f32x4*)(base + off + bj * HALF + n * 16); }
; #pragma unroll
;             for (int m = 0; m < 4; ++m) { const size_t off = (size_t)(row0 + ai * HALF + m * 16) * DM + col0;
; #pragma unroll
;                 for (int bj = 0; bj < 2; ++bj)
; #pragma unroll
;                     for (int n = 0; n < 2; ++n) *(f32x4*)(out + off + bj * HALF + n * 16) = bs[m][bj][n] + scale * acc[ai][bj][m][n]; }
;             asm volatile("" ::: "memory");
	v_pk_fma_f32 v[176:177], v[94:95], 0.5, v[222:223] op_sel_hi:[1,0,1]
	v_pk_fma_f32 v[174:175], v[92:93], 0.5, v[220:221] op_sel_hi:[1,0,1]
	global_store_dwordx4 v[190:191], v[174:177], off offset:512
	s_nop 1
	v_pk_fma_f32 v[176:177], v[90:91], 0.5, v[226:227] op_sel_hi:[1,0,1]
	v_pk_fma_f32 v[174:175], v[88:89], 0.5, v[224:225] op_sel_hi:[1,0,1]
	global_store_dwordx4 v[190:191], v[174:177], off offset:576
	s_nop 1
	v_pk_fma_f32 v[176:177], v[102:103], 0.5, v[230:231] op_sel_hi:[1,0,1]
	v_pk_fma_f32 v[174:175], v[100:101], 0.5, v[228:229] op_sel_hi:[1,0,1]
	global_store_dwordx4 v[188:189], v[174:177], off
	s_nop 1
	v_pk_fma_f32 v[176:177], v[98:99], 0.5, v[234:235] op_sel_hi:[1,0,1]
	v_pk_fma_f32 v[174:175], v[96:97], 0.5, v[232:233] op_sel_hi:[1,0,1]
	global_store_dwordx4 v[188:189], v[174:177], off offset:64
	s_nop 1
	v_pk_fma_f32 v[176:177], v[78:79], 0.5, v[238:239] op_sel_hi:[1,0,1]
	v_pk_fma_f32 v[174:175], v[76:77], 0.5, v[236:237] op_sel_hi:[1,0,1]
	global_store_dwordx4 v[188:189], v[174:177], off offset:512
	s_nop 1
	v_pk_fma_f32 v[176:177], v[74:75], 0.5, v[242:243] op_sel_hi:[1,0,1]
	v_pk_fma_f32 v[174:175], v[72:73], 0.5, v[240:241] op_sel_hi:[1,0,1]
	global_store_dwordx4 v[188:189], v[174:177], off offset:576
	s_nop 1
	v_pk_fma_f32 v[176:177], v[86:87], 0.5, v[246:247] op_sel_hi:[1,0,1]
	v_pk_fma_f32 v[174:175], v[84:85], 0.5, v[244:245] op_sel_hi:[1,0,1]
	global_store_dwordx4 v[168:169], v[174:177], off
	v_lshl_add_u64 v[168:169], v[166:167], 0, s[16:17]
	v_lshl_add_u64 v[128:129], v[164:165], 0, v[168:169]
	global_load_dwordx4 v[174:177], v[128:129], off
	global_load_dwordx4 v[200:203], v[128:129], off offset:64
	global_load_dwordx4 v[204:207], v[128:129], off offset:512
	global_load_dwordx4 v[208:211], v[128:129], off offset:576
	s_mov_b64 s[16:17], 0x120000
	v_lshl_add_u64 v[188:189], v[166:167], 0, s[16:17]
	v_lshl_add_u64 v[128:129], v[164:165], 0, v[188:189]
	global_load_dwordx4 v[212:215], v[128:129], off
	global_load_dwordx4 v[216:219], v[128:129], off offset:64
	global_load_dwordx4 v[220:223], v[128:129], off offset:512
	global_load_dwordx4 v[224:227], v[128:129], off offset:576
	s_mov_b64 s[16:17], 0x140000
	v_lshl_add_u64 v[190:191], v[166:167], 0, s[16:17]
	v_lshl_add_u64 v[128:129], v[164:165], 0, v[190:191]
	s_mov_b64 s[16:17], 0x160000
	global_load_dwordx4 v[228:231], v[128:129], off
	global_load_dwordx4 v[232:235], v[128:129], off offset:64
	global_load_dwordx4 v[236:239], v[128:129], off offset:512
	global_load_dwordx4 v[240:243], v[128:129], off offset:576
	v_lshl_add_u64 v[166:167], v[166:167], 0, s[16:17]
	v_lshl_add_u64 v[128:129], v[164:165], 0, v[166:167]
	global_load_dwordx4 v[244:247], v[128:129], off
	global_load_dwordx4 v[136:139], v[128:129], off offset:64
	global_load_dwordx4 v[132:135], v[128:129], off offset:512
	s_nop 0
	global_load_dwordx4 v[128:131], v[128:129], off offset:576
	v_lshl_add_u64 v[164:165], s[60:61], 0, v[168:169]
	v_lshl_add_u64 v[164:165], v[164:165], 0, v[162:163]
	s_mov_b64 s[16:17], 0
	s_waitcnt vmcnt(0)
	v_pk_fma_f32 v[176:177], v[62:63], 0.5, v[176:177] op_sel_hi:[1,0,1]
	v_pk_fma_f32 v[174:175], v[60:61], 0.5, v[174:175] op_sel_hi:[1,0,1]
	global_store_dwordx4 v[164:165], v[174:177], off
	v_pk_fma_f32 v[138:139], v[18:19], 0.5, v[138:139] op_sel_hi:[1,0,1]
	s_nop 0
	v_pk_fma_f32 v[176:177], v[58:59], 0.5, v[202:203] op_sel_hi:[1,0,1]
	v_pk_fma_f32 v[174:175], v[56:57], 0.5, v[200:201] op_sel_hi:[1,0,1]
	global_store_dwordx4 v[164:165], v[174:177], off offset:64
	v_pk_fma_f32 v[136:137], v[16:17], 0.5, v[136:137] op_sel_hi:[1,0,1]
	v_pk_fma_f32 v[134:135], v[6:7], 0.5, v[134:135] op_sel_hi:[1,0,1]
	v_pk_fma_f32 v[176:177], v[46:47], 0.5, v[206:207] op_sel_hi:[1,0,1]
	v_pk_fma_f32 v[174:175], v[44:45], 0.5, v[204:205] op_sel_hi:[1,0,1]
	global_store_dwordx4 v[164:165], v[174:177], off offset:512
	v_pk_fma_f32 v[132:133], v[4:5], 0.5, v[132:133] op_sel_hi:[1,0,1]
	v_pk_fma_f32 v[130:131], v[2:3], 0.5, v[130:131] op_sel_hi:[1,0,1]
	v_pk_fma_f32 v[176:177], v[42:43], 0.5, v[210:211] op_sel_hi:[1,0,1]
	v_pk_fma_f32 v[174:175], v[40:41], 0.5, v[208:209] op_sel_hi:[1,0,1]
	global_store_dwordx4 v[164:165], v[174:177], off offset:576
	v_lshl_add_u64 v[164:165], s[60:61], 0, v[188:189]
	v_lshl_add_u64 v[164:165], v[164:165], 0, v[162:163]
	v_pk_fma_f32 v[176:177], v[54:55], 0.5, v[214:215] op_sel_hi:[1,0,1]
	v_pk_fma_f32 v[174:175], v[52:53], 0.5, v[212:213] op_sel_hi:[1,0,1]
	global_store_dwordx4 v[164:165], v[174:177], off
	v_pk_fma_f32 v[128:129], v[0:1], 0.5, v[128:129] op_sel_hi:[1,0,1]
	s_nop 0
	v_pk_fma_f32 v[176:177], v[50:51], 0.5, v[218:219] op_sel_hi:[1,0,1]
	v_pk_fma_f32 v[174:175], v[48:49], 0.5, v[216:217] op_sel_hi:[1,0,1]
	global_store_dwordx4 v[164:165], v[174:177], off offset:64
	s_nop 1
	v_pk_fma_f32 v[176:177], v[30:31], 0.5, v[222:223] op_sel_hi:[1,0,1]
	v_pk_fma_f32 v[174:175], v[28:29], 0.5, v[220:221] op_sel_hi:[1,0,1]
	global_store_dwordx4 v[164:165], v[174:177], off offset:512
	s_nop 1
	v_pk_fma_f32 v[176:177], v[26:27], 0.5, v[226:227] op_sel_hi:[1,0,1]
	v_pk_fma_f32 v[174:175], v[24:25], 0.5, v[224:225] op_sel_hi:[1,0,1]
	global_store_dwordx4 v[164:165], v[174:177], off offset:576
	v_lshl_add_u64 v[164:165], s[60:61], 0, v[190:191]
	v_lshl_add_u64 v[164:165], v[164:165], 0, v[162:163]
	v_pk_fma_f32 v[176:177], v[38:39], 0.5, v[230:231] op_sel_hi:[1,0,1]
	v_pk_fma_f32 v[174:175], v[36:37], 0.5, v[228:229] op_sel_hi:[1,0,1]
	global_store_dwordx4 v[164:165], v[174:177], off
	s_nop 1
	v_pk_fma_f32 v[176:177], v[34:35], 0.5, v[234:235] op_sel_hi:[1,0,1]
	v_pk_fma_f32 v[174:175], v[32:33], 0.5, v[232:233] op_sel_hi:[1,0,1]
	global_store_dwordx4 v[164:165], v[174:177], off offset:64
	s_nop 1
	v_pk_fma_f32 v[176:177], v[14:15], 0.5, v[238:239] op_sel_hi:[1,0,1]
	v_pk_fma_f32 v[174:175], v[12:13], 0.5, v[236:237] op_sel_hi:[1,0,1]
	global_store_dwordx4 v[164:165], v[174:177], off offset:512
	s_nop 1
	v_pk_fma_f32 v[176:177], v[10:11], 0.5, v[242:243] op_sel_hi:[1,0,1]
	v_pk_fma_f32 v[174:175], v[8:9], 0.5, v[240:241] op_sel_hi:[1,0,1]
	global_store_dwordx4 v[164:165], v[174:177], off offset:576
	v_lshl_add_u64 v[164:165], s[60:61], 0, v[166:167]
	v_lshl_add_u64 v[162:163], v[164:165], 0, v[162:163]
	v_pk_fma_f32 v[176:177], v[22:23], 0.5, v[246:247] op_sel_hi:[1,0,1]
	v_pk_fma_f32 v[174:175], v[20:21], 0.5, v[244:245] op_sel_hi:[1,0,1]
	global_store_dwordx4 v[162:163], v[174:177], off
	global_store_dwordx4 v[162:163], v[136:139], off offset:64
	global_store_dwordx4 v[162:163], v[132:135], off offset:512
	global_store_dwordx4 v[162:163], v[128:131], off offset:576

; #define PG8_STAGE(bufoff, gbase, voff) do { _Pragma("unroll") for (int _i = 0; _i < 2; ++_i) \
;         __builtin_amdgcn_global_load_lds((const unsigned*)((const char*)(gbase) + (voff)[_i]), (LAS unsigned*)(lds + (bufoff) + ldsw + _i * 8192), 16, 0, 0); } while (0)
; #define PG8_LDA(dst, b, h) do { _Pragma("unroll") for (int m = 0; m < 4; ++m) _Pragma("unroll") for (int k = 0; k < 2; ++k) dst[m][k] = *(const LAS bf16x8*)(lds + PG8_SA(b, h) + aoff + m * 2048 + k * 1024); } while (0)
; #define PG8_LDB(dst, b, h) do { _Pragma("unroll") for (int n = 0; n < 2; ++n) _Pragma("unroll") for (int k = 0; k < 2; ++k) dst[n][k] = *(const LAS bf16x8*)(lds + PG8_SB(b, h) + boff + n * 2048 + k * 1024); } while (0)
; #define PG8_MMA(ai, bj, At, Bt) do { __builtin_amdgcn_s_setprio(1); _Pragma("unroll") for (int m = 0; m < 4; ++m) _Pragma("unroll") for (int n = 0; n < 2; ++n) _Pragma("unroll") for (int k = 0; k < 2; ++k) \
;         acc[ai][bj][m][n] = __builtin_amdgcn_mfma_f32_16x16x32_bf16(Bt[n][k], At[m][k], acc[ai][bj][m][n], 0, 0, 0); __builtin_amdgcn_s_setprio(0); } while (0)
; #define PG8_WAIT_V(n) asm volatile("s_waitcnt vmcnt(" #n ")" ::: "memory")
; #define PG8_WAIT_L(n) asm volatile("s_waitcnt lgkmcnt(" #n ")" ::: "memory")
; #define PG8_BAR __builtin_amdgcn_s_barrier()
; template <class Epi, class Sched>
; __device__ __forceinline__ void gemm_phase(LAS unsigned char* lds, const Gemm g, const Sched& S, const Epi& E) {
;     ...
;             const bool last = (t == nt - 2);
;             const char* a1 = cA + (size_t)(t + 1) * kstep;
;             const char* a2 = last ? nA : cA + (size_t)(t + 2) * kstep; const char* b2 = last ? nB : cB + (size_t)(t + 2) * kstep;
;             const char* a3 = a2 + kstep; const char* b3 = b2 + kstep;
;             PG8_LDB(B0, 0, 0); PG8_SCHED; PG8_LDA(At, 0, 0); PG8_STAGE(PG8_SA(1, 1), a1 + hstep, voffA);
;             PG8_WAIT_L(8); PG8_BAR; PG8_WAIT_L(0); PG8_MMA(0, 0, At, B0); PG8_BAR; PG8_SCHED;
;             PG8_LDB(B1, 0, 1); PG8_STAGE(PG8_SB(0, 0), b2, voffB);
;             PG8_BAR; PG8_WAIT_L(0); PG8_MMA(0, 1, At, B1); PG8_BAR;
;             PG8_LDA(At, 0, 1); PG8_STAGE(PG8_SA(0, 0), a2, voffA);
;             PG8_BAR; PG8_WAIT_L(0); PG8_MMA(1, 0, At, B0); PG8_BAR; PG8_SCHED;
;             PG8_STAGE(PG8_SB(0, 1), b2 + hstep, voffB);
;             PG8_WAIT_V(6); PG8_BAR; PG8_MMA(1, 1, At, B1); PG8_BAR;
.LBB0_213:
	s_add_u32 s20, s16, 0xfff80080
	s_addc_u32 s21, s17, -1
	s_add_i32 s45, 0, 0x10000
	ds_read_b128 v[144:147], v129
	ds_read_b128 v[160:163], v129 offset:1024
	ds_read_b128 v[164:167], v129 offset:2048
	ds_read_b128 v[168:171], v129 offset:3072
	s_cmp_eq_u32 s44, 28
	s_cselect_b32 s23, s11, s21
	s_cselect_b32 s22, s40, s20
	s_cselect_b32 s21, s7, s43
	s_cselect_b32 s20, s41, s42
	s_add_i32 m0, s30, 0xc000
	ds_read_b128 v[172:175], v143
	ds_read_b128 v[200:203], v143 offset:1024
	ds_read_b128 v[204:207], v143 offset:2048
	ds_read_b128 v[208:211], v143 offset:3072
	ds_read_b128 v[212:215], v143 offset:4096
	ds_read_b128 v[216:219], v143 offset:5120
	ds_read_b128 v[220:223], v143 offset:6144
	ds_read_b128 v[224:227], v143 offset:7168
	global_load_lds_dwordx4 v134, s[16:17]
	s_add_i32 m0, s30, 0xe000
	s_nop 0
	global_load_lds_dwordx4 v136, s[16:17]
	s_waitcnt lgkmcnt(8)
	s_barrier
	s_waitcnt lgkmcnt(0)
	v_mfma_f32_16x16x32_bf16 v[124:127], v[144:147], v[172:175], v[124:127]
	v_mfma_f32_16x16x32_bf16 v[116:119], v[164:167], v[172:175], v[116:119]
	v_mfma_f32_16x16x32_bf16 v[108:111], v[144:147], v[204:207], v[108:111]
	v_mfma_f32_16x16x32_bf16 v[100:103], v[164:167], v[204:207], v[100:103]
	v_mfma_f32_16x16x32_bf16 v[92:95], v[144:147], v[212:215], v[92:95]
	v_mfma_f32_16x16x32_bf16 v[84:87], v[164:167], v[212:215], v[84:87]
	v_mfma_f32_16x16x32_bf16 v[76:79], v[144:147], v[220:223], v[76:79]
	v_mfma_f32_16x16x32_bf16 v[68:71], v[164:167], v[220:223], v[68:71]
	v_mfma_f32_16x16x32_bf16 v[124:127], v[160:163], v[200:203], v[124:127]
	v_mfma_f32_16x16x32_bf16 v[116:119], v[168:171], v[200:203], v[116:119]
	v_mfma_f32_16x16x32_bf16 v[108:111], v[160:163], v[208:211], v[108:111]
	v_mfma_f32_16x16x32_bf16 v[100:103], v[168:171], v[208:211], v[100:103]
	v_mfma_f32_16x16x32_bf16 v[92:95], v[160:163], v[216:219], v[92:95]
	v_mfma_f32_16x16x32_bf16 v[84:87], v[168:171], v[216:219], v[84:87]
	v_mfma_f32_16x16x32_bf16 v[76:79], v[160:163], v[224:227], v[76:79]
	v_mfma_f32_16x16x32_bf16 v[68:71], v[168:171], v[224:227], v[68:71]
	s_barrier
	s_add_i32 s48, 0, 0x14000
	s_add_i32 s45, s45, s29
	ds_read_b128 v[228:231], v129 offset:16384
	ds_read_b128 v[232:235], v129 offset:17408
	ds_read_b128 v[236:239], v129 offset:18432
	ds_read_b128 v[240:243], v129 offset:19456
	s_add_u32 s84, s20, 0x80
	s_addc_u32 s85, s21, 0
	s_mov_b32 m0, s45
	s_nop 0
	global_load_lds_dwordx4 v148, s[20:21]
	s_add_i32 m0, s45, 0x2000
	s_nop 0
	global_load_lds_dwordx4 v128, s[20:21]
	s_waitcnt lgkmcnt(0)
	s_barrier
	v_mfma_f32_16x16x32_bf16 v[120:123], v[228:231], v[172:175], v[120:123]
	v_mfma_f32_16x16x32_bf16 v[112:115], v[236:239], v[172:175], v[112:115]
	v_mfma_f32_16x16x32_bf16 v[104:107], v[228:231], v[204:207], v[104:107]
	v_mfma_f32_16x16x32_bf16 v[96:99], v[236:239], v[204:207], v[96:99]
	v_mfma_f32_16x16x32_bf16 v[88:91], v[228:231], v[212:215], v[88:91]
	v_mfma_f32_16x16x32_bf16 v[80:83], v[236:239], v[212:215], v[80:83]
	v_mfma_f32_16x16x32_bf16 v[72:75], v[228:231], v[220:223], v[72:75]
	v_mfma_f32_16x16x32_bf16 v[64:67], v[236:239], v[220:223], v[64:67]
	v_mfma_f32_16x16x32_bf16 v[120:123], v[232:235], v[200:203], v[120:123]
	v_mfma_f32_16x16x32_bf16 v[112:115], v[240:243], v[200:203], v[112:115]
	v_mfma_f32_16x16x32_bf16 v[104:107], v[232:235], v[208:211], v[104:107]
	v_mfma_f32_16x16x32_bf16 v[96:99], v[240:243], v[208:211], v[96:99]
	v_mfma_f32_16x16x32_bf16 v[88:91], v[232:235], v[216:219], v[88:91]
	v_mfma_f32_16x16x32_bf16 v[80:83], v[240:243], v[216:219], v[80:83]
	v_mfma_f32_16x16x32_bf16 v[72:75], v[232:235], v[224:227], v[72:75]
	v_mfma_f32_16x16x32_bf16 v[64:67], v[240:243], v[224:227], v[64:67]
	s_mov_b32 m0, s30
	s_add_u32 s86, s22, 0x80
	s_addc_u32 s87, s23, 0
	s_barrier
	ds_read_b128 v[172:175], v143 offset:16384
	ds_read_b128 v[200:203], v143 offset:17408
	ds_read_b128 v[204:207], v143 offset:18432
	ds_read_b128 v[208:211], v143 offset:19456
	ds_read_b128 v[212:215], v143 offset:20480
	ds_read_b128 v[216:219], v143 offset:21504
	ds_read_b128 v[220:223], v143 offset:22528
	ds_read_b128 v[224:227], v143 offset:23552
	global_load_lds_dwordx4 v132, s[22:23]
	s_mov_b32 m0, s31
	s_nop 0
	global_load_lds_dwordx4 v130, s[22:23]
	s_waitcnt lgkmcnt(0)
	s_barrier
	v_mfma_f32_16x16x32_bf16 v[60:63], v[144:147], v[172:175], v[60:63]
	v_mfma_f32_16x16x32_bf16 v[52:55], v[164:167], v[172:175], v[52:55]
	v_mfma_f32_16x16x32_bf16 v[44:47], v[144:147], v[204:207], v[44:47]
	v_mfma_f32_16x16x32_bf16 v[36:39], v[164:167], v[204:207], v[36:39]
	v_mfma_f32_16x16x32_bf16 v[28:31], v[144:147], v[212:215], v[28:31]
	v_mfma_f32_16x16x32_bf16 v[20:23], v[164:167], v[212:215], v[20:23]
	v_mfma_f32_16x16x32_bf16 v[12:15], v[144:147], v[220:223], v[12:15]
	v_mfma_f32_16x16x32_bf16 v[4:7], v[164:167], v[220:223], v[4:7]
	v_mfma_f32_16x16x32_bf16 v[60:63], v[160:163], v[200:203], v[60:63]
	v_mfma_f32_16x16x32_bf16 v[52:55], v[168:171], v[200:203], v[52:55]
	v_mfma_f32_16x16x32_bf16 v[44:47], v[160:163], v[208:211], v[44:47]
	v_mfma_f32_16x16x32_bf16 v[36:39], v[168:171], v[208:211], v[36:39]
	v_mfma_f32_16x16x32_bf16 v[28:31], v[160:163], v[216:219], v[28:31]
	v_mfma_f32_16x16x32_bf16 v[20:23], v[168:171], v[216:219], v[20:23]
	v_mfma_f32_16x16x32_bf16 v[12:15], v[160:163], v[224:227], v[12:15]
	v_mfma_f32_16x16x32_bf16 v[4:7], v[168:171], v[224:227], v[4:7]
	s_barrier
	s_add_u32 s46, s20, 0x80000
	s_addc_u32 s47, s21, 0
	s_add_i32 s45, s48, s29
	s_mov_b32 m0, s45
	s_nop 0
	global_load_lds_dwordx4 v148, s[46:47]
	s_add_i32 m0, s45, 0x2000
	s_nop 0
	global_load_lds_dwordx4 v128, s[46:47]
	s_waitcnt vmcnt(6)
	s_barrier
; #define PG8_STAGE(bufoff, gbase, voff) do { _Pragma("unroll") for (int _i = 0; _i < 2; ++_i) \
;         __builtin_amdgcn_global_load_lds((const unsigned*)((const char*)(gbase) + (voff)[_i]), (LAS unsigned*)(lds + (bufoff) + ldsw + _i * 8192), 16, 0, 0); } while (0)
; #define PG8_LDA(dst, b, h) do { _Pragma("unroll") for (int m = 0; m < 4; ++m) _Pragma("unroll") for (int k = 0; k < 2; ++k) dst[m][k] = *(const LAS bf16x8*)(lds + PG8_SA(b, h) + aoff + m * 2048 + k * 1024); } while (0)
; #define PG8_LDB(dst, b, h) do { _Pragma("unroll") for (int n = 0; n < 2; ++n) _Pragma("unroll") for (int k = 0; k < 2; ++k) dst[n][k] = *(const LAS bf16x8*)(lds + PG8_SB(b, h) + boff + n * 2048 + k * 1024); } while (0)
; #define PG8_MMA(ai, bj, At, Bt) do { __builtin_amdgcn_s_setprio(1); _Pragma("unroll") for (int m = 0; m < 4; ++m) _Pragma("unroll") for (int n = 0; n < 2; ++n) _Pragma("unroll") for (int k = 0; k < 2; ++k) \
;         acc[ai][bj][m][n] = __builtin_amdgcn_mfma_f32_16x16x32_bf16(Bt[n][k], At[m][k], acc[ai][bj][m][n], 0, 0, 0); __builtin_amdgcn_s_setprio(0); } while (0)
; #define PG8_WAIT_V(n) asm volatile("s_waitcnt vmcnt(" #n ")" ::: "memory")
; #define PG8_WAIT_L(n) asm volatile("s_waitcnt lgkmcnt(" #n ")" ::: "memory")
; #define PG8_BAR __builtin_amdgcn_s_barrier()
; #define PG8_SCHED __builtin_amdgcn_sched_barrier(0)
; template <class Epi, class Sched>
; __device__ __forceinline__ void gemm_phase(LAS unsigned char* lds, const Gemm g, const Sched& S, const Epi& E) {
;     ...
;             PG8_WAIT_V(6); PG8_BAR; PG8_MMA(1, 1, At, B1); PG8_BAR;
;             PG8_LDB(B0, 1, 0); PG8_SCHED; PG8_LDA(At, 1, 0); PG8_STAGE(PG8_SA(0, 1), a2 + hstep, voffA);
;             PG8_WAIT_L(8); PG8_BAR; PG8_WAIT_L(0); PG8_MMA(0, 0, At, B0); PG8_BAR; PG8_SCHED;
;             PG8_LDB(B1, 1, 1); PG8_STAGE(PG8_SB(1, 0), b3, voffB);
;             PG8_BAR; PG8_WAIT_L(0); PG8_MMA(0, 1, At, B1); PG8_BAR;
;             PG8_LDA(At, 1, 1); PG8_STAGE(PG8_SA(1, 0), a3, voffA);
;             PG8_BAR; PG8_WAIT_L(0); PG8_MMA(1, 0, At, B0); PG8_BAR; PG8_SCHED;
	v_mfma_f32_16x16x32_bf16 v[56:59], v[228:231], v[172:175], v[56:59]
	v_mfma_f32_16x16x32_bf16 v[48:51], v[236:239], v[172:175], v[48:51]
	v_mfma_f32_16x16x32_bf16 v[40:43], v[228:231], v[204:207], v[40:43]
	v_mfma_f32_16x16x32_bf16 v[32:35], v[236:239], v[204:207], v[32:35]
	v_mfma_f32_16x16x32_bf16 v[24:27], v[228:231], v[212:215], v[24:27]
	v_mfma_f32_16x16x32_bf16 v[16:19], v[236:239], v[212:215], v[16:19]
	v_mfma_f32_16x16x32_bf16 v[8:11], v[228:231], v[220:223], v[8:11]
	v_mfma_f32_16x16x32_bf16 v[0:3], v[236:239], v[220:223], v[0:3]
	v_mfma_f32_16x16x32_bf16 v[56:59], v[232:235], v[200:203], v[56:59]
	v_mfma_f32_16x16x32_bf16 v[48:51], v[240:243], v[200:203], v[48:51]
	v_mfma_f32_16x16x32_bf16 v[40:43], v[232:235], v[208:211], v[40:43]
	v_mfma_f32_16x16x32_bf16 v[32:35], v[240:243], v[208:211], v[32:35]
	v_mfma_f32_16x16x32_bf16 v[24:27], v[232:235], v[216:219], v[24:27]
	v_mfma_f32_16x16x32_bf16 v[16:19], v[240:243], v[216:219], v[16:19]
	v_mfma_f32_16x16x32_bf16 v[8:11], v[232:235], v[224:227], v[8:11]
	v_mfma_f32_16x16x32_bf16 v[0:3], v[240:243], v[224:227], v[0:3]
	s_add_i32 s45, 0, 0x18000
	s_barrier
	ds_read_b128 v[144:147], v129 offset:32768
	ds_read_b128 v[160:163], v129 offset:33792
	ds_read_b128 v[164:167], v129 offset:34816
	ds_read_b128 v[168:171], v129 offset:35840
	s_add_u32 s22, s22, 0x80000
	s_addc_u32 s23, s23, 0
	s_mov_b32 m0, s33
	ds_read_b128 v[172:175], v143 offset:32768
	ds_read_b128 v[200:203], v143 offset:33792
	ds_read_b128 v[204:207], v143 offset:34816
	ds_read_b128 v[208:211], v143 offset:35840
	ds_read_b128 v[212:215], v143 offset:36864
	ds_read_b128 v[216:219], v143 offset:37888
	ds_read_b128 v[220:223], v143 offset:38912
	ds_read_b128 v[224:227], v143 offset:39936
	global_load_lds_dwordx4 v132, s[22:23]
	s_mov_b32 m0, s34
	s_nop 0
	global_load_lds_dwordx4 v130, s[22:23]
	s_waitcnt lgkmcnt(8)
	s_barrier
	s_waitcnt lgkmcnt(0)
	v_mfma_f32_16x16x32_bf16 v[124:127], v[144:147], v[172:175], v[124:127]
	v_mfma_f32_16x16x32_bf16 v[116:119], v[164:167], v[172:175], v[116:119]
	v_mfma_f32_16x16x32_bf16 v[108:111], v[144:147], v[204:207], v[108:111]
	v_mfma_f32_16x16x32_bf16 v[100:103], v[164:167], v[204:207], v[100:103]
	v_mfma_f32_16x16x32_bf16 v[92:95], v[144:147], v[212:215], v[92:95]
	v_mfma_f32_16x16x32_bf16 v[84:87], v[164:167], v[212:215], v[84:87]
	v_mfma_f32_16x16x32_bf16 v[76:79], v[144:147], v[220:223], v[76:79]
	v_mfma_f32_16x16x32_bf16 v[68:71], v[164:167], v[220:223], v[68:71]
	v_mfma_f32_16x16x32_bf16 v[124:127], v[160:163], v[200:203], v[124:127]
	v_mfma_f32_16x16x32_bf16 v[116:119], v[168:171], v[200:203], v[116:119]
	v_mfma_f32_16x16x32_bf16 v[108:111], v[160:163], v[208:211], v[108:111]
	v_mfma_f32_16x16x32_bf16 v[100:103], v[168:171], v[208:211], v[100:103]
	v_mfma_f32_16x16x32_bf16 v[92:95], v[160:163], v[216:219], v[92:95]
	v_mfma_f32_16x16x32_bf16 v[84:87], v[168:171], v[216:219], v[84:87]
	v_mfma_f32_16x16x32_bf16 v[76:79], v[160:163], v[224:227], v[76:79]
	v_mfma_f32_16x16x32_bf16 v[68:71], v[168:171], v[224:227], v[68:71]
	s_barrier
	s_add_i32 s22, 0, 0x1c000
	s_add_i32 s23, s45, s29
	s_mov_b32 m0, s23
	ds_read_b128 v[228:231], v129 offset:49152
	ds_read_b128 v[232:235], v129 offset:50176
	ds_read_b128 v[236:239], v129 offset:51200
	ds_read_b128 v[240:243], v129 offset:52224
	global_load_lds_dwordx4 v148, s[84:85]
	s_add_i32 m0, s23, 0x2000
	s_nop 0
	global_load_lds_dwordx4 v128, s[84:85]
	s_waitcnt lgkmcnt(0)
	s_barrier
	v_mfma_f32_16x16x32_bf16 v[120:123], v[228:231], v[172:175], v[120:123]
	v_mfma_f32_16x16x32_bf16 v[112:115], v[236:239], v[172:175], v[112:115]
	v_mfma_f32_16x16x32_bf16 v[104:107], v[228:231], v[204:207], v[104:107]
	v_mfma_f32_16x16x32_bf16 v[96:99], v[236:239], v[204:207], v[96:99]
	v_mfma_f32_16x16x32_bf16 v[88:91], v[228:231], v[212:215], v[88:91]
	v_mfma_f32_16x16x32_bf16 v[80:83], v[236:239], v[212:215], v[80:83]
	v_mfma_f32_16x16x32_bf16 v[72:75], v[228:231], v[220:223], v[72:75]
	v_mfma_f32_16x16x32_bf16 v[64:67], v[236:239], v[220:223], v[64:67]
	v_mfma_f32_16x16x32_bf16 v[120:123], v[232:235], v[200:203], v[120:123]
	v_mfma_f32_16x16x32_bf16 v[112:115], v[240:243], v[200:203], v[112:115]
	v_mfma_f32_16x16x32_bf16 v[104:107], v[232:235], v[208:211], v[104:107]
	v_mfma_f32_16x16x32_bf16 v[96:99], v[240:243], v[208:211], v[96:99]
	v_mfma_f32_16x16x32_bf16 v[88:91], v[232:235], v[216:219], v[88:91]
	v_mfma_f32_16x16x32_bf16 v[80:83], v[240:243], v[216:219], v[80:83]
	v_mfma_f32_16x16x32_bf16 v[72:75], v[232:235], v[224:227], v[72:75]
	v_mfma_f32_16x16x32_bf16 v[64:67], v[240:243], v[224:227], v[64:67]
	s_mov_b32 m0, s35
	s_barrier
	ds_read_b128 v[172:175], v143 offset:49152
	ds_read_b128 v[200:203], v143 offset:50176
	ds_read_b128 v[204:207], v143 offset:51200
	ds_read_b128 v[208:211], v143 offset:52224
	ds_read_b128 v[212:215], v143 offset:53248
	ds_read_b128 v[216:219], v143 offset:54272
	ds_read_b128 v[220:223], v143 offset:55296
	ds_read_b128 v[224:227], v143 offset:56320
	global_load_lds_dwordx4 v132, s[86:87]
	s_mov_b32 m0, s36
	s_nop 0
	global_load_lds_dwordx4 v130, s[86:87]
	s_waitcnt lgkmcnt(0)
	s_barrier
; __device__ __forceinline__ unsigned cvt_pk_bf16(float lo, float hi) { unsigned r; asm("v_cvt_pk_bf16_f32 %0, %1, %2" : "=v"(r) : "v"(lo), "v"(hi)); return r; }
; #define PG8_STAGE(bufoff, gbase, voff) do { _Pragma("unroll") for (int _i = 0; _i < 2; ++_i) \
;         __builtin_amdgcn_global_load_lds((const unsigned*)((const char*)(gbase) + (voff)[_i]), (LAS unsigned*)(lds + (bufoff) + ldsw + _i * 8192), 16, 0, 0); } while (0)
; #define PG8_MMA(ai, bj, At, Bt) do { __builtin_amdgcn_s_setprio(1); _Pragma("unroll") for (int m = 0; m < 4; ++m) _Pragma("unroll") for (int n = 0; n < 2; ++n) _Pragma("unroll") for (int k = 0; k < 2; ++k) \
;         acc[ai][bj][m][n] = __builtin_amdgcn_mfma_f32_16x16x32_bf16(Bt[n][k], At[m][k], acc[ai][bj][m][n], 0, 0, 0); __builtin_amdgcn_s_setprio(0); } while (0)
; #define PG8_WAIT_V(n) asm volatile("s_waitcnt vmcnt(" #n ")" ::: "memory")
; #define PG8_BAR __builtin_amdgcn_s_barrier()
;     __device__ __forceinline__ void operator()(const f32x4 (&acc)[2][2][4][2], const Unit& u, int wr, int wc, int fr, int fq) const {
;         const int row0 = u.pm * BM + wr * 64 + fr, col0 = u.pn * HALF + wc * 32 + 8 * fq;
; #pragma unroll
;         for (int ai = 0; ai < 2; ++ai)
; #pragma unroll
;             for (int m = 0; m < 4; ++m) { bf16_t* rowp = O + (size_t)(row0 + ai * HALF + m * 16) * ldc + col0;
;                 float h[8];
; #pragma unroll
;                 for (int n = 0; n < 2; ++n)
; #pragma unroll
;                     for (int j = 0; j < 4; ++j) { const float g = acc[ai][0][m][n][j], up = acc[ai][1][m][n][j];
;                         const float e = __builtin_amdgcn_exp2f(-1.4426950408889634f * g);
;                         h[n * 4 + j] = g * __builtin_amdgcn_rcpf(1.0f + e) * up; }
;                 u32x4 w; w.x = cvt_pk_bf16(h[0], h[1]); w.y = cvt_pk_bf16(h[2], h[3]); w.z = cvt_pk_bf16(h[4], h[5]); w.w = cvt_pk_bf16(h[6], h[7]);
;                 *(u32x4*)rowp = w; }
; template <class Epi, class Sched>
; __device__ __forceinline__ void gemm_phase(LAS unsigned char* lds, const Gemm g, const Sched& S, const Epi& E) {
;     ...
;             PG8_STAGE(PG8_SB(1, 1), b3 + hstep, voffB);
;             PG8_WAIT_V(6); PG8_BAR; PG8_MMA(1, 1, At, B1); PG8_BAR;
	v_mfma_f32_16x16x32_bf16 v[60:63], v[144:147], v[172:175], v[60:63]
	v_mfma_f32_16x16x32_bf16 v[52:55], v[164:167], v[172:175], v[52:55]
	v_mfma_f32_16x16x32_bf16 v[44:47], v[144:147], v[204:207], v[44:47]
	v_mfma_f32_16x16x32_bf16 v[36:39], v[164:167], v[204:207], v[36:39]
	v_mfma_f32_16x16x32_bf16 v[28:31], v[144:147], v[212:215], v[28:31]
	v_mfma_f32_16x16x32_bf16 v[20:23], v[164:167], v[212:215], v[20:23]
	v_mfma_f32_16x16x32_bf16 v[12:15], v[144:147], v[220:223], v[12:15]
	v_mfma_f32_16x16x32_bf16 v[4:7], v[164:167], v[220:223], v[4:7]
	v_mfma_f32_16x16x32_bf16 v[60:63], v[160:163], v[200:203], v[60:63]
	v_mfma_f32_16x16x32_bf16 v[52:55], v[168:171], v[200:203], v[52:55]
	v_mfma_f32_16x16x32_bf16 v[44:47], v[160:163], v[208:211], v[44:47]
	v_mfma_f32_16x16x32_bf16 v[36:39], v[168:171], v[208:211], v[36:39]
	v_mfma_f32_16x16x32_bf16 v[28:31], v[160:163], v[216:219], v[28:31]
	v_mfma_f32_16x16x32_bf16 v[20:23], v[168:171], v[216:219], v[20:23]
	v_mfma_f32_16x16x32_bf16 v[12:15], v[160:163], v[224:227], v[12:15]
	v_mfma_f32_16x16x32_bf16 v[4:7], v[168:171], v[224:227], v[4:7]
	s_barrier
	s_add_u32 s20, s20, 0x80080
	s_addc_u32 s21, s21, 0
	s_add_i32 s22, s22, s29
	s_mov_b32 m0, s22
	s_nop 0
	global_load_lds_dwordx4 v148, s[20:21]
	s_add_i32 m0, s22, 0x2000
	s_nop 0
	global_load_lds_dwordx4 v128, s[20:21]
	s_waitcnt vmcnt(6)
	s_barrier
	v_mfma_f32_16x16x32_bf16 v[56:59], v[228:231], v[172:175], v[56:59]
	v_mfma_f32_16x16x32_bf16 v[48:51], v[236:239], v[172:175], v[48:51]
	v_mfma_f32_16x16x32_bf16 v[40:43], v[228:231], v[204:207], v[40:43]
	v_mfma_f32_16x16x32_bf16 v[32:35], v[236:239], v[204:207], v[32:35]
	v_mfma_f32_16x16x32_bf16 v[24:27], v[228:231], v[212:215], v[24:27]
	v_mfma_f32_16x16x32_bf16 v[16:19], v[236:239], v[212:215], v[16:19]
	v_mfma_f32_16x16x32_bf16 v[8:11], v[228:231], v[220:223], v[8:11]
	v_mfma_f32_16x16x32_bf16 v[0:3], v[236:239], v[220:223], v[0:3]
	v_mfma_f32_16x16x32_bf16 v[56:59], v[232:235], v[200:203], v[56:59]
	v_mfma_f32_16x16x32_bf16 v[48:51], v[240:243], v[200:203], v[48:51]
	v_mfma_f32_16x16x32_bf16 v[40:43], v[232:235], v[208:211], v[40:43]
	v_mfma_f32_16x16x32_bf16 v[32:35], v[240:243], v[208:211], v[32:35]
	v_mfma_f32_16x16x32_bf16 v[24:27], v[232:235], v[216:219], v[24:27]
	v_mfma_f32_16x16x32_bf16 v[16:19], v[240:243], v[216:219], v[16:19]
	v_mfma_f32_16x16x32_bf16 v[8:11], v[232:235], v[224:227], v[8:11]
	v_mfma_f32_16x16x32_bf16 v[0:3], v[240:243], v[224:227], v[0:3]
	s_add_i32 s44, s44, 2
	s_add_u32 s16, s16, 0x100
	s_addc_u32 s17, s17, 0
	s_add_u32 s42, s42, 0x100
	s_addc_u32 s43, s43, 0
	s_cmp_gt_u32 s44, 29
	s_barrier
	s_cbranch_scc0 .LBB0_213
	v_mul_f32_e32 v145, 0xbfb8aa3b, v124
	v_exp_f32_e32 v145, v145
	v_lshl_or_b32 v146, s38, 7, v142
	v_lshl_add_u32 v144, s39, 8, v140
	v_ashrrev_i32_e32 v147, 31, v146
	v_add_f32_e32 v145, 1.0, v145
	v_rcp_f32_e32 v145, v145
	v_mov_b64_e32 v[138:139], s[4:5]
	s_movk_i32 s7, 0x2c00
	v_mad_i64_i32 v[160:161], s[16:17], v144, s7, v[138:139]
	v_mul_f32_e32 v124, v124, v145
	v_mul_f32_e32 v120, v120, v124
	v_mul_f32_e32 v124, 0xbfb8aa3b, v125
	v_exp_f32_e32 v124, v124
	s_and_b64 vcc, exec, s[0:1]
	s_mov_b32 s38, s6
	s_mov_b32 s39, s10
	v_add_f32_e32 v124, 1.0, v124
	v_rcp_f32_e32 v124, v124
	s_mov_b64 s[20:21], s[14:15]
	v_mul_f32_e32 v124, v125, v124
	v_mul_f32_e32 v121, v121, v124
	v_mul_f32_e32 v124, 0xbfb8aa3b, v126
	v_exp_f32_e32 v124, v124
	s_nop 0
	v_add_f32_e32 v124, 1.0, v124
	v_rcp_f32_e32 v124, v124
	s_nop 0
	v_mul_f32_e32 v124, v126, v124
	v_mul_f32_e32 v122, v122, v124
	v_mul_f32_e32 v124, 0xbfb8aa3b, v127
	v_exp_f32_e32 v124, v124
	s_nop 0
	v_add_f32_e32 v124, 1.0, v124
	v_rcp_f32_e32 v124, v124
	s_nop 0
	v_mul_f32_e32 v124, v127, v124
	v_mul_f32_e32 v123, v123, v124
	v_mul_f32_e32 v124, 0xbfb8aa3b, v116
	v_exp_f32_e32 v124, v124
	s_nop 0
	v_add_f32_e32 v124, 1.0, v124
	v_rcp_f32_e32 v124, v124
	s_nop 0
	v_mul_f32_e32 v116, v116, v124
	v_mul_f32_e32 v116, v112, v116
	v_mul_f32_e32 v112, 0xbfb8aa3b, v117
	v_exp_f32_e32 v112, v112
	s_nop 0
	v_add_f32_e32 v112, 1.0, v112
	v_rcp_f32_e32 v112, v112
	s_nop 0
	v_mul_f32_e32 v112, v117, v112
	v_mul_f32_e32 v117, v113, v112
	v_mul_f32_e32 v112, 0xbfb8aa3b, v118
	v_exp_f32_e32 v112, v112
	v_cvt_pk_bf16_f32 v116, v116, v117
	s_nop 0
	v_add_f32_e32 v112, 1.0, v112
	v_rcp_f32_e32 v112, v112
	s_nop 0
	v_mul_f32_e32 v112, v118, v112
	v_mul_f32_e32 v124, v114, v112
	v_mul_f32_e32 v112, 0xbfb8aa3b, v119
	v_exp_f32_e32 v112, v112
	v_cvt_pk_bf16_f32 v114, v120, v121
	s_nop 0
	v_add_f32_e32 v112, 1.0, v112
	v_rcp_f32_e32 v112, v112
	s_nop 0
	v_mul_f32_e32 v112, v119, v112
	v_mul_f32_e32 v125, v115, v112
	v_lshlrev_b64 v[112:113], 1, v[146:147]
	v_lshl_add_u64 v[118:119], v[160:161], 0, v[112:113]
	v_cvt_pk_bf16_f32 v115, v122, v123
	v_cvt_pk_bf16_f32 v117, v124, v125
	global_store_dwordx4 v[118:119], v[114:117], off
	s_nop 1
	v_mul_f32_e32 v116, 0xbfb8aa3b, v108
	v_exp_f32_e32 v116, v116
	v_or_b32_e32 v114, 16, v144
	v_mad_i64_i32 v[114:115], s[16:17], v114, s7, v[138:139]
	v_add_f32_e32 v116, 1.0, v116
	v_rcp_f32_e32 v116, v116
	s_nop 0
	v_mul_f32_e32 v108, v108, v116
	v_mul_f32_e32 v104, v104, v108
	v_mul_f32_e32 v108, 0xbfb8aa3b, v109
	v_exp_f32_e32 v108, v108
	s_nop 0
	v_add_f32_e32 v108, 1.0, v108
	v_rcp_f32_e32 v108, v108
	s_nop 0
	v_mul_f32_e32 v108, v109, v108
	v_mul_f32_e32 v105, v105, v108
	v_mul_f32_e32 v108, 0xbfb8aa3b, v110
	v_exp_f32_e32 v108, v108
	s_nop 0
	v_add_f32_e32 v108, 1.0, v108
	v_rcp_f32_e32 v108, v108
	s_nop 0
	v_mul_f32_e32 v108, v110, v108
	v_mul_f32_e32 v106, v106, v108
	v_mul_f32_e32 v108, 0xbfb8aa3b, v111
	v_exp_f32_e32 v108, v108
	s_nop 0
	v_add_f32_e32 v108, 1.0, v108
; __device__ __forceinline__ unsigned cvt_pk_bf16(float lo, float hi) { unsigned r; asm("v_cvt_pk_bf16_f32 %0, %1, %2" : "=v"(r) : "v"(lo), "v"(hi)); return r; }
;     __device__ __forceinline__ void operator()(const f32x4 (&acc)[2][2][4][2], const Unit& u, int wr, int wc, int fr, int fq) const {
;     ...
;         for (int ai = 0; ai < 2; ++ai)
; #pragma unroll
;             for (int m = 0; m < 4; ++m) { bf16_t* rowp = O + (size_t)(row0 + ai * HALF + m * 16) * ldc + col0;
;                 float h[8];
; #pragma unroll
;                 for (int n = 0; n < 2; ++n)
; #pragma unroll
;                     for (int j = 0; j < 4; ++j) { const float g = acc[ai][0][m][n][j], up = acc[ai][1][m][n][j];
;                         const float e = __builtin_amdgcn_exp2f(-1.4426950408889634f * g);
;                         h[n * 4 + j] = g * __builtin_amdgcn_rcpf(1.0f + e) * up; }
;                 u32x4 w; w.x = cvt_pk_bf16(h[0], h[1]); w.y = cvt_pk_bf16(h[2], h[3]); w.z = cvt_pk_bf16(h[4], h[5]); w.w = cvt_pk_bf16(h[6], h[7]);
;                 *(u32x4*)rowp = w; }
	v_rcp_f32_e32 v108, v108
	s_nop 0
	v_mul_f32_e32 v108, v111, v108
	v_mul_f32_e32 v107, v107, v108
	v_mul_f32_e32 v108, 0xbfb8aa3b, v100
	v_exp_f32_e32 v108, v108
	s_nop 0
	v_add_f32_e32 v108, 1.0, v108
	v_rcp_f32_e32 v108, v108
	s_nop 0
	v_mul_f32_e32 v100, v100, v108
	v_mul_f32_e32 v108, v96, v100
	v_mul_f32_e32 v96, 0xbfb8aa3b, v101
	v_exp_f32_e32 v96, v96
	s_nop 0
	v_add_f32_e32 v96, 1.0, v96
	v_rcp_f32_e32 v96, v96
	s_nop 0
	v_mul_f32_e32 v96, v101, v96
	v_mul_f32_e32 v109, v97, v96
	v_mul_f32_e32 v96, 0xbfb8aa3b, v102
	v_exp_f32_e32 v96, v96
	v_lshl_add_u64 v[100:101], v[114:115], 0, v[112:113]
	v_cvt_pk_bf16_f32 v97, v106, v107
	v_add_f32_e32 v96, 1.0, v96
	v_rcp_f32_e32 v96, v96
	s_nop 0
	v_mul_f32_e32 v96, v102, v96
	v_mul_f32_e32 v102, v98, v96
	v_mul_f32_e32 v96, 0xbfb8aa3b, v103
	v_exp_f32_e32 v96, v96
	v_cvt_pk_bf16_f32 v98, v108, v109
	s_nop 0
	v_add_f32_e32 v96, 1.0, v96
	v_rcp_f32_e32 v96, v96
	s_nop 0
	v_mul_f32_e32 v96, v103, v96
	v_mul_f32_e32 v99, v99, v96
	v_cvt_pk_bf16_f32 v96, v104, v105
	v_cvt_pk_bf16_f32 v99, v102, v99
	global_store_dwordx4 v[100:101], v[96:99], off
	s_nop 1
	v_mul_f32_e32 v98, 0xbfb8aa3b, v92
	v_exp_f32_e32 v98, v98
	v_or_b32_e32 v96, 32, v144
	v_mad_i64_i32 v[96:97], s[16:17], v96, s7, v[138:139]
	v_add_f32_e32 v98, 1.0, v98
	v_rcp_f32_e32 v98, v98
	s_nop 0
	v_mul_f32_e32 v92, v92, v98
	v_mul_f32_e32 v88, v88, v92
	v_mul_f32_e32 v92, 0xbfb8aa3b, v93
	v_exp_f32_e32 v92, v92
	s_nop 0
	v_add_f32_e32 v92, 1.0, v92
	v_rcp_f32_e32 v92, v92
	s_nop 0
	v_mul_f32_e32 v92, v93, v92
	v_mul_f32_e32 v89, v89, v92
	v_mul_f32_e32 v92, 0xbfb8aa3b, v94
	v_exp_f32_e32 v92, v92
	s_nop 0
	v_add_f32_e32 v92, 1.0, v92
	v_rcp_f32_e32 v92, v92
	s_nop 0
	v_mul_f32_e32 v92, v94, v92
	v_mul_f32_e32 v90, v90, v92
	v_mul_f32_e32 v92, 0xbfb8aa3b, v95
	v_exp_f32_e32 v92, v92
	s_nop 0
	v_add_f32_e32 v92, 1.0, v92
	v_rcp_f32_e32 v92, v92
	s_nop 0
	v_mul_f32_e32 v92, v95, v92
	v_mul_f32_e32 v91, v91, v92
	v_mul_f32_e32 v92, 0xbfb8aa3b, v84
	v_exp_f32_e32 v92, v92
	s_nop 0
	v_add_f32_e32 v92, 1.0, v92
	v_rcp_f32_e32 v92, v92
	s_nop 0
	v_mul_f32_e32 v84, v84, v92
	v_mul_f32_e32 v92, v80, v84
	v_mul_f32_e32 v80, 0xbfb8aa3b, v85
	v_exp_f32_e32 v80, v80
	s_nop 0
	v_add_f32_e32 v80, 1.0, v80
	v_rcp_f32_e32 v80, v80
	s_nop 0
	v_mul_f32_e32 v80, v85, v80
	v_mul_f32_e32 v93, v81, v80
	v_mul_f32_e32 v80, 0xbfb8aa3b, v86
	v_exp_f32_e32 v80, v80
	v_lshl_add_u64 v[84:85], v[96:97], 0, v[112:113]
	v_cvt_pk_bf16_f32 v81, v90, v91
	v_add_f32_e32 v80, 1.0, v80
	v_rcp_f32_e32 v80, v80
	s_nop 0
	v_mul_f32_e32 v80, v86, v80
	v_mul_f32_e32 v86, v82, v80
	v_mul_f32_e32 v80, 0xbfb8aa3b, v87
	v_exp_f32_e32 v80, v80
	v_cvt_pk_bf16_f32 v82, v92, v93
	s_nop 0
	v_add_f32_e32 v80, 1.0, v80
	v_rcp_f32_e32 v80, v80
	s_nop 0
	v_mul_f32_e32 v80, v87, v80
	v_mul_f32_e32 v83, v83, v80
	v_cvt_pk_bf16_f32 v80, v88, v89
	v_cvt_pk_bf16_f32 v83, v86, v83
	global_store_dwordx4 v[84:85], v[80:83], off
	s_nop 1
	v_mul_f32_e32 v82, 0xbfb8aa3b, v76
	v_exp_f32_e32 v82, v82
	v_or_b32_e32 v80, 48, v144
	v_mad_i64_i32 v[80:81], s[16:17], v80, s7, v[138:139]
	v_add_f32_e32 v82, 1.0, v82
	v_rcp_f32_e32 v82, v82
	s_nop 0
	v_mul_f32_e32 v76, v76, v82
	v_mul_f32_e32 v72, v72, v76
	v_mul_f32_e32 v76, 0xbfb8aa3b, v77
	v_exp_f32_e32 v76, v76
	s_nop 0
	v_add_f32_e32 v76, 1.0, v76
	v_rcp_f32_e32 v76, v76
	s_nop 0
	v_mul_f32_e32 v76, v77, v76
	v_mul_f32_e32 v73, v73, v76
	v_mul_f32_e32 v76, 0xbfb8aa3b, v78
	v_exp_f32_e32 v76, v76
	s_nop 0
	v_add_f32_e32 v76, 1.0, v76
	v_rcp_f32_e32 v76, v76
	s_nop 0
	v_mul_f32_e32 v76, v78, v76
	v_mul_f32_e32 v74, v74, v76
	v_mul_f32_e32 v76, 0xbfb8aa3b, v79
	v_exp_f32_e32 v76, v76
	s_nop 0
	v_add_f32_e32 v76, 1.0, v76
	v_rcp_f32_e32 v76, v76
	s_nop 0
	v_mul_f32_e32 v76, v79, v76
	v_mul_f32_e32 v75, v75, v76
	v_mul_f32_e32 v76, 0xbfb8aa3b, v68
	v_exp_f32_e32 v76, v76
	s_nop 0
	v_add_f32_e32 v76, 1.0, v76
	v_rcp_f32_e32 v76, v76
	s_nop 0
	v_mul_f32_e32 v68, v68, v76
	v_mul_f32_e32 v76, v64, v68
	v_mul_f32_e32 v64, 0xbfb8aa3b, v69
	v_exp_f32_e32 v64, v64
	s_nop 0
	v_add_f32_e32 v64, 1.0, v64
	v_rcp_f32_e32 v64, v64
	s_nop 0
	v_mul_f32_e32 v64, v69, v64
	v_mul_f32_e32 v77, v65, v64
	v_mul_f32_e32 v64, 0xbfb8aa3b, v70
	v_exp_f32_e32 v64, v64
	v_lshl_add_u64 v[68:69], v[80:81], 0, v[112:113]
	v_cvt_pk_bf16_f32 v65, v74, v75
	v_add_f32_e32 v64, 1.0, v64
	v_rcp_f32_e32 v64, v64
	s_nop 0
	v_mul_f32_e32 v64, v70, v64
	v_mul_f32_e32 v70, v66, v64
	v_mul_f32_e32 v64, 0xbfb8aa3b, v71
	v_exp_f32_e32 v64, v64
	v_cvt_pk_bf16_f32 v66, v76, v77
	s_nop 0
	v_add_f32_e32 v64, 1.0, v64
	v_rcp_f32_e32 v64, v64
	s_nop 0
	v_mul_f32_e32 v64, v71, v64
	v_mul_f32_e32 v67, v67, v64
	v_cvt_pk_bf16_f32 v64, v72, v73
	v_cvt_pk_bf16_f32 v67, v70, v67
	global_store_dwordx4 v[68:69], v[64:67], off
	s_nop 1
	v_mul_f32_e32 v66, 0xbfb8aa3b, v60
	v_exp_f32_e32 v66, v66
	v_add_u32_e32 v64, 0x80, v144
	v_mad_i64_i32 v[64:65], s[16:17], v64, s7, v[138:139]
	v_add_f32_e32 v66, 1.0, v66
	v_rcp_f32_e32 v66, v66
	s_nop 0
	v_mul_f32_e32 v60, v60, v66
	v_mul_f32_e32 v56, v56, v60
	v_mul_f32_e32 v60, 0xbfb8aa3b, v61
	v_exp_f32_e32 v60, v60
	s_nop 0
	v_add_f32_e32 v60, 1.0, v60
	v_rcp_f32_e32 v60, v60
	s_nop 0
	v_mul_f32_e32 v60, v61, v60
	v_mul_f32_e32 v57, v57, v60
	v_mul_f32_e32 v60, 0xbfb8aa3b, v62
	v_exp_f32_e32 v60, v60
	s_nop 0
	v_add_f32_e32 v60, 1.0, v60
	v_rcp_f32_e32 v60, v60
	s_nop 0
	v_mul_f32_e32 v60, v62, v60
	v_mul_f32_e32 v58, v58, v60
	v_mul_f32_e32 v60, 0xbfb8aa3b, v63
	v_exp_f32_e32 v60, v60
	s_nop 0
	v_add_f32_e32 v60, 1.0, v60
	v_rcp_f32_e32 v60, v60
	s_nop 0
	v_mul_f32_e32 v60, v63, v60
	v_mul_f32_e32 v59, v59, v60
	v_mul_f32_e32 v60, 0xbfb8aa3b, v52
	v_exp_f32_e32 v60, v60
; __device__ __forceinline__ unsigned cvt_pk_bf16(float lo, float hi) { unsigned r; asm("v_cvt_pk_bf16_f32 %0, %1, %2" : "=v"(r) : "v"(lo), "v"(hi)); return r; }
;     __device__ __forceinline__ void operator()(const f32x4 (&acc)[2][2][4][2], const Unit& u, int wr, int wc, int fr, int fq) const {
;     ...
;         for (int ai = 0; ai < 2; ++ai)
; #pragma unroll
;             for (int m = 0; m < 4; ++m) { bf16_t* rowp = O + (size_t)(row0 + ai * HALF + m * 16) * ldc + col0;
;                 float h[8];
; #pragma unroll
;                 for (int n = 0; n < 2; ++n)
; #pragma unroll
;                     for (int j = 0; j < 4; ++j) { const float g = acc[ai][0][m][n][j], up = acc[ai][1][m][n][j];
;                         const float e = __builtin_amdgcn_exp2f(-1.4426950408889634f * g);
;                         h[n * 4 + j] = g * __builtin_amdgcn_rcpf(1.0f + e) * up; }
;                 u32x4 w; w.x = cvt_pk_bf16(h[0], h[1]); w.y = cvt_pk_bf16(h[2], h[3]); w.z = cvt_pk_bf16(h[4], h[5]); w.w = cvt_pk_bf16(h[6], h[7]);
;                 *(u32x4*)rowp = w; }
	s_nop 0
	v_add_f32_e32 v60, 1.0, v60
	v_rcp_f32_e32 v60, v60
	s_nop 0
	v_mul_f32_e32 v52, v52, v60
	v_mul_f32_e32 v60, v48, v52
	v_mul_f32_e32 v48, 0xbfb8aa3b, v53
	v_exp_f32_e32 v48, v48
	s_nop 0
	v_add_f32_e32 v48, 1.0, v48
	v_rcp_f32_e32 v48, v48
	s_nop 0
	v_mul_f32_e32 v48, v53, v48
	v_mul_f32_e32 v61, v49, v48
	v_mul_f32_e32 v48, 0xbfb8aa3b, v54
	v_exp_f32_e32 v48, v48
	v_lshl_add_u64 v[52:53], v[64:65], 0, v[112:113]
	v_cvt_pk_bf16_f32 v49, v58, v59
	v_add_f32_e32 v48, 1.0, v48
	v_rcp_f32_e32 v48, v48
	s_nop 0
	v_mul_f32_e32 v48, v54, v48
	v_mul_f32_e32 v54, v50, v48
	v_mul_f32_e32 v48, 0xbfb8aa3b, v55
	v_exp_f32_e32 v48, v48
	v_cvt_pk_bf16_f32 v50, v60, v61
	s_nop 0
	v_add_f32_e32 v48, 1.0, v48
	v_rcp_f32_e32 v48, v48
	s_nop 0
	v_mul_f32_e32 v48, v55, v48
	v_mul_f32_e32 v51, v51, v48
	v_cvt_pk_bf16_f32 v48, v56, v57
	v_cvt_pk_bf16_f32 v51, v54, v51
	global_store_dwordx4 v[52:53], v[48:51], off
	s_nop 1
	v_mul_f32_e32 v50, 0xbfb8aa3b, v44
	v_exp_f32_e32 v50, v50
	v_add_u32_e32 v48, 0x90, v144
	v_mad_i64_i32 v[48:49], s[16:17], v48, s7, v[138:139]
	v_add_f32_e32 v50, 1.0, v50
	v_rcp_f32_e32 v50, v50
	s_nop 0
	v_mul_f32_e32 v44, v44, v50
	v_mul_f32_e32 v40, v40, v44
	v_mul_f32_e32 v44, 0xbfb8aa3b, v45
	v_exp_f32_e32 v44, v44
	s_nop 0
	v_add_f32_e32 v44, 1.0, v44
	v_rcp_f32_e32 v44, v44
	s_nop 0
	v_mul_f32_e32 v44, v45, v44
	v_mul_f32_e32 v41, v41, v44
	v_mul_f32_e32 v44, 0xbfb8aa3b, v46
	v_exp_f32_e32 v44, v44
	s_nop 0
	v_add_f32_e32 v44, 1.0, v44
	v_rcp_f32_e32 v44, v44
	s_nop 0
	v_mul_f32_e32 v44, v46, v44
	v_mul_f32_e32 v42, v42, v44
	v_mul_f32_e32 v44, 0xbfb8aa3b, v47
	v_exp_f32_e32 v44, v44
	s_nop 0
	v_add_f32_e32 v44, 1.0, v44
	v_rcp_f32_e32 v44, v44
	s_nop 0
	v_mul_f32_e32 v44, v47, v44
	v_mul_f32_e32 v43, v43, v44
	v_mul_f32_e32 v44, 0xbfb8aa3b, v36
	v_exp_f32_e32 v44, v44
	s_nop 0
	v_add_f32_e32 v44, 1.0, v44
	v_rcp_f32_e32 v44, v44
	s_nop 0
	v_mul_f32_e32 v36, v36, v44
	v_mul_f32_e32 v44, v32, v36
	v_mul_f32_e32 v32, 0xbfb8aa3b, v37
	v_exp_f32_e32 v32, v32
	s_nop 0
	v_add_f32_e32 v32, 1.0, v32
	v_rcp_f32_e32 v32, v32
	s_nop 0
	v_mul_f32_e32 v32, v37, v32
	v_mul_f32_e32 v45, v33, v32
	v_mul_f32_e32 v32, 0xbfb8aa3b, v38
	v_exp_f32_e32 v32, v32
	v_lshl_add_u64 v[36:37], v[48:49], 0, v[112:113]
	v_cvt_pk_bf16_f32 v33, v42, v43
	v_add_f32_e32 v32, 1.0, v32
	v_rcp_f32_e32 v32, v32
	s_nop 0
	v_mul_f32_e32 v32, v38, v32
	v_mul_f32_e32 v38, v34, v32
	v_mul_f32_e32 v32, 0xbfb8aa3b, v39
	v_exp_f32_e32 v32, v32
	v_cvt_pk_bf16_f32 v34, v44, v45
	s_nop 0
	v_add_f32_e32 v32, 1.0, v32
	v_rcp_f32_e32 v32, v32
	s_nop 0
	v_mul_f32_e32 v32, v39, v32
	v_mul_f32_e32 v35, v35, v32
	v_cvt_pk_bf16_f32 v32, v40, v41
	v_cvt_pk_bf16_f32 v35, v38, v35
	global_store_dwordx4 v[36:37], v[32:35], off
	s_nop 1
	v_mul_f32_e32 v34, 0xbfb8aa3b, v28
	v_exp_f32_e32 v34, v34
	v_add_u32_e32 v32, 0xa0, v144
	v_mad_i64_i32 v[32:33], s[16:17], v32, s7, v[138:139]
	v_add_f32_e32 v34, 1.0, v34
	v_rcp_f32_e32 v34, v34
	s_nop 0
	v_mul_f32_e32 v28, v28, v34
	v_mul_f32_e32 v24, v24, v28
	v_mul_f32_e32 v28, 0xbfb8aa3b, v29
	v_exp_f32_e32 v28, v28
	s_nop 0
	v_add_f32_e32 v28, 1.0, v28
	v_rcp_f32_e32 v28, v28
	s_nop 0
	v_mul_f32_e32 v28, v29, v28
	v_mul_f32_e32 v25, v25, v28
	v_mul_f32_e32 v28, 0xbfb8aa3b, v30
	v_exp_f32_e32 v28, v28
	s_nop 0
	v_add_f32_e32 v28, 1.0, v28
	v_rcp_f32_e32 v28, v28
	s_nop 0
	v_mul_f32_e32 v28, v30, v28
	v_mul_f32_e32 v26, v26, v28
	v_mul_f32_e32 v28, 0xbfb8aa3b, v31
	v_exp_f32_e32 v28, v28
	s_nop 0
	v_add_f32_e32 v28, 1.0, v28
	v_rcp_f32_e32 v28, v28
	s_nop 0
	v_mul_f32_e32 v28, v31, v28
	v_mul_f32_e32 v27, v27, v28
	v_mul_f32_e32 v28, 0xbfb8aa3b, v20
	v_exp_f32_e32 v28, v28
	s_nop 0
	v_add_f32_e32 v28, 1.0, v28
	v_rcp_f32_e32 v28, v28
	s_nop 0
	v_mul_f32_e32 v20, v20, v28
	v_mul_f32_e32 v28, v16, v20
	v_mul_f32_e32 v16, 0xbfb8aa3b, v21
	v_exp_f32_e32 v16, v16
	s_nop 0
	v_add_f32_e32 v16, 1.0, v16
	v_rcp_f32_e32 v16, v16
	s_nop 0
	v_mul_f32_e32 v16, v21, v16
	v_mul_f32_e32 v29, v17, v16
	v_mul_f32_e32 v16, 0xbfb8aa3b, v22
	v_exp_f32_e32 v16, v16
	v_lshl_add_u64 v[20:21], v[32:33], 0, v[112:113]
	v_cvt_pk_bf16_f32 v17, v26, v27
	v_add_f32_e32 v16, 1.0, v16
	v_rcp_f32_e32 v16, v16
	s_nop 0
	v_mul_f32_e32 v16, v22, v16
	v_mul_f32_e32 v22, v18, v16
	v_mul_f32_e32 v16, 0xbfb8aa3b, v23
	v_exp_f32_e32 v16, v16
	v_cvt_pk_bf16_f32 v18, v28, v29
	s_nop 0
	v_add_f32_e32 v16, 1.0, v16
	v_rcp_f32_e32 v16, v16
	s_nop 0
	v_mul_f32_e32 v16, v23, v16
	v_mul_f32_e32 v19, v19, v16
	v_cvt_pk_bf16_f32 v16, v24, v25
	v_cvt_pk_bf16_f32 v19, v22, v19
	global_store_dwordx4 v[20:21], v[16:19], off
	s_nop 1
	v_mul_f32_e32 v18, 0xbfb8aa3b, v12
	v_exp_f32_e32 v18, v18
	v_add_u32_e32 v16, 0xb0, v144
	v_mad_i64_i32 v[16:17], s[16:17], v16, s7, v[138:139]
	v_add_f32_e32 v18, 1.0, v18
	v_rcp_f32_e32 v18, v18
	s_mov_b64 s[16:17], s[12:13]
	v_mul_f32_e32 v12, v12, v18
	v_mul_f32_e32 v8, v8, v12
	v_mul_f32_e32 v12, 0xbfb8aa3b, v13
	v_exp_f32_e32 v12, v12
	s_nop 0
	v_add_f32_e32 v12, 1.0, v12
	v_rcp_f32_e32 v12, v12
	s_nop 0
	v_mul_f32_e32 v12, v13, v12
	v_mul_f32_e32 v9, v9, v12
	v_mul_f32_e32 v12, 0xbfb8aa3b, v14
	v_exp_f32_e32 v12, v12
	s_nop 0
	v_add_f32_e32 v12, 1.0, v12
	v_rcp_f32_e32 v12, v12
	s_nop 0
	v_mul_f32_e32 v12, v14, v12
	v_mul_f32_e32 v10, v10, v12
	v_mul_f32_e32 v12, 0xbfb8aa3b, v15
	v_exp_f32_e32 v12, v12
	s_nop 0
	v_add_f32_e32 v12, 1.0, v12
	v_rcp_f32_e32 v12, v12
	s_nop 0
	v_mul_f32_e32 v12, v15, v12
	v_mul_f32_e32 v11, v11, v12
	v_mul_f32_e32 v12, 0xbfb8aa3b, v4
	v_exp_f32_e32 v12, v12
	s_nop 0
	v_add_f32_e32 v12, 1.0, v12
	v_rcp_f32_e32 v12, v12
	s_nop 0
	v_mul_f32_e32 v4, v4, v12
	v_mul_f32_e32 v12, v0, v4
	v_mul_f32_e32 v0, 0xbfb8aa3b, v5
	v_exp_f32_e32 v0, v0
	s_nop 0
	v_add_f32_e32 v0, 1.0, v0
	v_rcp_f32_e32 v0, v0
	s_nop 0
	v_mul_f32_e32 v0, v5, v0
	v_mul_f32_e32 v13, v1, v0
	v_mul_f32_e32 v0, 0xbfb8aa3b, v6
	v_exp_f32_e32 v0, v0
	v_lshl_add_u64 v[4:5], v[16:17], 0, v[112:113]
	v_cvt_pk_bf16_f32 v1, v10, v11
	v_add_f32_e32 v0, 1.0, v0
	v_rcp_f32_e32 v0, v0
	s_nop 0
	v_mul_f32_e32 v0, v6, v0
	v_mul_f32_e32 v6, v2, v0
	v_mul_f32_e32 v0, 0xbfb8aa3b, v7
	v_exp_f32_e32 v0, v0
	v_cvt_pk_bf16_f32 v2, v12, v13
	s_nop 0
	v_add_f32_e32 v0, 1.0, v0
	v_rcp_f32_e32 v0, v0
	s_nop 0
	v_mul_f32_e32 v0, v7, v0
	v_mul_f32_e32 v3, v3, v0
	v_cvt_pk_bf16_f32 v0, v8, v9
	v_cvt_pk_bf16_f32 v3, v6, v3
	global_store_dwordx4 v[4:5], v[0:3], off
	s_cbranch_vccz .LBB0_210
	s_waitcnt vmcnt(0)
	s_cmpk_gt_u32 s24, 0xff
	s_cbranch_scc1 .LBB0_217
	s_barrier

; #define PG8_STAGE(bufoff, gbase, voff) do { _Pragma("unroll") for (int _i = 0; _i < 2; ++_i) \
;         __builtin_amdgcn_global_load_lds((const unsigned*)((const char*)(gbase) + (voff)[_i]), (LAS unsigned*)(lds + (bufoff) + ldsw + _i * 8192), 16, 0, 0); } while (0)
; #define PG8_LDA(dst, b, h) do { _Pragma("unroll") for (int m = 0; m < 4; ++m) _Pragma("unroll") for (int k = 0; k < 2; ++k) dst[m][k] = *(const LAS bf16x8*)(lds + PG8_SA(b, h) + aoff + m * 2048 + k * 1024); } while (0)
; #define PG8_LDB(dst, b, h) do { _Pragma("unroll") for (int n = 0; n < 2; ++n) _Pragma("unroll") for (int k = 0; k < 2; ++k) dst[n][k] = *(const LAS bf16x8*)(lds + PG8_SB(b, h) + boff + n * 2048 + k * 1024); } while (0)
; #define PG8_MMA(ai, bj, At, Bt) do { __builtin_amdgcn_s_setprio(1); _Pragma("unroll") for (int m = 0; m < 4; ++m) _Pragma("unroll") for (int n = 0; n < 2; ++n) _Pragma("unroll") for (int k = 0; k < 2; ++k) \
;         acc[ai][bj][m][n] = __builtin_amdgcn_mfma_f32_16x16x32_bf16(Bt[n][k], At[m][k], acc[ai][bj][m][n], 0, 0, 0); __builtin_amdgcn_s_setprio(0); } while (0)
; #define PG8_WAIT_V(n) asm volatile("s_waitcnt vmcnt(" #n ")" ::: "memory")
; #define PG8_WAIT_L(n) asm volatile("s_waitcnt lgkmcnt(" #n ")" ::: "memory")
; template <class Epi, class Sched>
; __device__ __forceinline__ void gemm_phase(LAS unsigned char* lds, const Gemm g, const Sched& S, const Epi& E) {
;     ...
;         for (int t = 0; t < nt; t += 2) {
;             const bool last = (t == nt - 2);
;             const char* a1 = cA + (size_t)(t + 1) * kstep;
;             const char* a2 = last ? nA : cA + (size_t)(t + 2) * kstep; const char* b2 = last ? nB : cB + (size_t)(t + 2) * kstep;
;             const char* a3 = a2 + kstep; const char* b3 = b2 + kstep;
;             PG8_LDB(B0, 0, 0); PG8_SCHED; PG8_LDA(At, 0, 0); PG8_STAGE(PG8_SA(1, 1), a1 + hstep, voffA);
;             PG8_WAIT_L(8); PG8_BAR; PG8_WAIT_L(0); PG8_MMA(0, 0, At, B0); PG8_BAR; PG8_SCHED;
;             PG8_LDB(B1, 0, 1); PG8_STAGE(PG8_SB(0, 0), b2, voffB);
;             PG8_BAR; PG8_WAIT_L(0); PG8_MMA(0, 1, At, B1); PG8_BAR;
;             PG8_LDA(At, 0, 1); PG8_STAGE(PG8_SA(0, 0), a2, voffA);
;             PG8_BAR; PG8_WAIT_L(0); PG8_MMA(1, 0, At, B0); PG8_BAR; PG8_SCHED;
;             PG8_STAGE(PG8_SB(0, 1), b2 + hstep, voffB);
;             PG8_WAIT_V(6); PG8_BAR; PG8_MMA(1, 1, At, B1); PG8_BAR;
.LBB0_267:
	s_add_i32 s47, s22, 2
	s_add_u32 s20, s16, 0x100
	s_addc_u32 s21, s17, 0
	s_add_i32 s48, 0, 0x10000
	ds_read_b128 v[128:131], v161
	ds_read_b128 v[132:135], v161 offset:1024
	ds_read_b128 v[136:139], v161 offset:2048
	ds_read_b128 v[140:143], v161 offset:3072
	s_cmp_eq_u32 s11, s22
	s_cselect_b32 s22, s4, s13
	s_cselect_b32 s25, s7, s21
	s_cselect_b32 s24, s6, s20
	s_cselect_b32 s23, s5, s15
	s_add_i32 m0, s33, 0xc000
	ds_read_b128 v[144:147], v203
	ds_read_b128 v[166:169], v203 offset:1024
	ds_read_b128 v[170:173], v203 offset:2048
	ds_read_b128 v[174:177], v203 offset:3072
	ds_read_b128 v[204:207], v203 offset:4096
	ds_read_b128 v[208:211], v203 offset:5120
	ds_read_b128 v[212:215], v203 offset:6144
	ds_read_b128 v[216:219], v203 offset:7168
	global_load_lds_dwordx4 v162, s[16:17]
	s_add_i32 m0, s33, 0xe000
	s_nop 0
	global_load_lds_dwordx4 v164, s[16:17]
	s_waitcnt lgkmcnt(8)
	s_barrier
	s_waitcnt lgkmcnt(0)
	v_mfma_f32_16x16x32_bf16 v[124:127], v[128:131], v[144:147], v[124:127]
	v_mfma_f32_16x16x32_bf16 v[120:123], v[136:139], v[144:147], v[120:123]
	v_mfma_f32_16x16x32_bf16 v[116:119], v[128:131], v[170:173], v[116:119]
	v_mfma_f32_16x16x32_bf16 v[112:115], v[136:139], v[170:173], v[112:115]
	v_mfma_f32_16x16x32_bf16 v[100:103], v[128:131], v[204:207], v[100:103]
	v_mfma_f32_16x16x32_bf16 v[96:99], v[136:139], v[204:207], v[96:99]
	v_mfma_f32_16x16x32_bf16 v[84:87], v[128:131], v[212:215], v[84:87]
	v_mfma_f32_16x16x32_bf16 v[80:83], v[136:139], v[212:215], v[80:83]
	v_mfma_f32_16x16x32_bf16 v[124:127], v[132:135], v[166:169], v[124:127]
	v_mfma_f32_16x16x32_bf16 v[120:123], v[140:143], v[166:169], v[120:123]
	v_mfma_f32_16x16x32_bf16 v[116:119], v[132:135], v[174:177], v[116:119]
	v_mfma_f32_16x16x32_bf16 v[112:115], v[140:143], v[174:177], v[112:115]
	v_mfma_f32_16x16x32_bf16 v[100:103], v[132:135], v[208:211], v[100:103]
	v_mfma_f32_16x16x32_bf16 v[96:99], v[140:143], v[208:211], v[96:99]
	v_mfma_f32_16x16x32_bf16 v[84:87], v[132:135], v[216:219], v[84:87]
	v_mfma_f32_16x16x32_bf16 v[80:83], v[140:143], v[216:219], v[80:83]
	s_barrier
	s_add_i32 s49, 0, 0x14000
	s_add_i32 s16, s48, s31
	ds_read_b128 v[220:223], v161 offset:16384
	ds_read_b128 v[224:227], v161 offset:17408
	ds_read_b128 v[228:231], v161 offset:18432
	ds_read_b128 v[232:235], v161 offset:19456
	s_add_u32 s84, s22, 0x80
	s_addc_u32 s85, s23, 0
	s_mov_b32 m0, s16
	s_nop 0
	global_load_lds_dwordx4 v148, s[22:23]
	s_add_i32 m0, s16, 0x2000
	s_nop 0
	global_load_lds_dwordx4 v160, s[22:23]
	s_waitcnt lgkmcnt(0)
	s_barrier
	v_mfma_f32_16x16x32_bf16 v[108:111], v[220:223], v[144:147], v[108:111]
	v_mfma_f32_16x16x32_bf16 v[104:107], v[228:231], v[144:147], v[104:107]
	v_mfma_f32_16x16x32_bf16 v[92:95], v[220:223], v[170:173], v[92:95]
	v_mfma_f32_16x16x32_bf16 v[88:91], v[228:231], v[170:173], v[88:91]
	v_mfma_f32_16x16x32_bf16 v[76:79], v[220:223], v[204:207], v[76:79]
	v_mfma_f32_16x16x32_bf16 v[72:75], v[228:231], v[204:207], v[72:75]
	v_mfma_f32_16x16x32_bf16 v[68:71], v[220:223], v[212:215], v[68:71]
	v_mfma_f32_16x16x32_bf16 v[64:67], v[228:231], v[212:215], v[64:67]
	v_mfma_f32_16x16x32_bf16 v[108:111], v[224:227], v[166:169], v[108:111]
	v_mfma_f32_16x16x32_bf16 v[104:107], v[232:235], v[166:169], v[104:107]
	v_mfma_f32_16x16x32_bf16 v[92:95], v[224:227], v[174:177], v[92:95]
	v_mfma_f32_16x16x32_bf16 v[88:91], v[232:235], v[174:177], v[88:91]
	v_mfma_f32_16x16x32_bf16 v[76:79], v[224:227], v[208:211], v[76:79]
	v_mfma_f32_16x16x32_bf16 v[72:75], v[232:235], v[208:211], v[72:75]
	v_mfma_f32_16x16x32_bf16 v[68:71], v[224:227], v[216:219], v[68:71]
	v_mfma_f32_16x16x32_bf16 v[64:67], v[232:235], v[216:219], v[64:67]
	s_mov_b32 m0, s33
	s_add_u32 s86, s24, 0x80
	s_addc_u32 s87, s25, 0
	s_barrier
	ds_read_b128 v[144:147], v203 offset:16384
	ds_read_b128 v[166:169], v203 offset:17408
	ds_read_b128 v[170:173], v203 offset:18432
	ds_read_b128 v[174:177], v203 offset:19456
	ds_read_b128 v[204:207], v203 offset:20480
	ds_read_b128 v[208:211], v203 offset:21504
	ds_read_b128 v[212:215], v203 offset:22528
	ds_read_b128 v[216:219], v203 offset:23552
	global_load_lds_dwordx4 v148, s[24:25]
	s_mov_b32 m0, s34
	s_nop 0
	global_load_lds_dwordx4 v160, s[24:25]
	s_waitcnt lgkmcnt(0)
	s_barrier
	v_mfma_f32_16x16x32_bf16 v[60:63], v[128:131], v[144:147], v[60:63]
	v_mfma_f32_16x16x32_bf16 v[56:59], v[136:139], v[144:147], v[56:59]
	v_mfma_f32_16x16x32_bf16 v[52:55], v[128:131], v[170:173], v[52:55]
	v_mfma_f32_16x16x32_bf16 v[48:51], v[136:139], v[170:173], v[48:51]
	v_mfma_f32_16x16x32_bf16 v[36:39], v[128:131], v[204:207], v[36:39]
	v_mfma_f32_16x16x32_bf16 v[32:35], v[136:139], v[204:207], v[32:35]
	v_mfma_f32_16x16x32_bf16 v[20:23], v[128:131], v[212:215], v[20:23]
	v_mfma_f32_16x16x32_bf16 v[16:19], v[136:139], v[212:215], v[16:19]
	v_mfma_f32_16x16x32_bf16 v[60:63], v[132:135], v[166:169], v[60:63]
	v_mfma_f32_16x16x32_bf16 v[56:59], v[140:143], v[166:169], v[56:59]
	v_mfma_f32_16x16x32_bf16 v[52:55], v[132:135], v[174:177], v[52:55]
	v_mfma_f32_16x16x32_bf16 v[48:51], v[140:143], v[174:177], v[48:51]
	v_mfma_f32_16x16x32_bf16 v[36:39], v[132:135], v[208:211], v[36:39]
	v_mfma_f32_16x16x32_bf16 v[32:35], v[140:143], v[208:211], v[32:35]
	v_mfma_f32_16x16x32_bf16 v[20:23], v[132:135], v[216:219], v[20:23]
	v_mfma_f32_16x16x32_bf16 v[16:19], v[140:143], v[216:219], v[16:19]
	s_barrier
	s_add_u32 s16, s22, 0x80000
	s_addc_u32 s17, s23, 0
	s_add_i32 s48, s49, s31
	s_mov_b32 m0, s48
	s_nop 0
	global_load_lds_dwordx4 v148, s[16:17]
	s_add_i32 m0, s48, 0x2000
	s_nop 0
	global_load_lds_dwordx4 v160, s[16:17]
	s_waitcnt vmcnt(6)
	s_barrier
; #define PG8_STAGE(bufoff, gbase, voff) do { _Pragma("unroll") for (int _i = 0; _i < 2; ++_i) \
;         __builtin_amdgcn_global_load_lds((const unsigned*)((const char*)(gbase) + (voff)[_i]), (LAS unsigned*)(lds + (bufoff) + ldsw + _i * 8192), 16, 0, 0); } while (0)
; #define PG8_LDA(dst, b, h) do { _Pragma("unroll") for (int m = 0; m < 4; ++m) _Pragma("unroll") for (int k = 0; k < 2; ++k) dst[m][k] = *(const LAS bf16x8*)(lds + PG8_SA(b, h) + aoff + m * 2048 + k * 1024); } while (0)
; #define PG8_LDB(dst, b, h) do { _Pragma("unroll") for (int n = 0; n < 2; ++n) _Pragma("unroll") for (int k = 0; k < 2; ++k) dst[n][k] = *(const LAS bf16x8*)(lds + PG8_SB(b, h) + boff + n * 2048 + k * 1024); } while (0)
; #define PG8_MMA(ai, bj, At, Bt) do { __builtin_amdgcn_s_setprio(1); _Pragma("unroll") for (int m = 0; m < 4; ++m) _Pragma("unroll") for (int n = 0; n < 2; ++n) _Pragma("unroll") for (int k = 0; k < 2; ++k) \
;         acc[ai][bj][m][n] = __builtin_amdgcn_mfma_f32_16x16x32_bf16(Bt[n][k], At[m][k], acc[ai][bj][m][n], 0, 0, 0); __builtin_amdgcn_s_setprio(0); } while (0)
; #define PG8_WAIT_V(n) asm volatile("s_waitcnt vmcnt(" #n ")" ::: "memory")
; #define PG8_WAIT_L(n) asm volatile("s_waitcnt lgkmcnt(" #n ")" ::: "memory")
; #define PG8_BAR __builtin_amdgcn_s_barrier()
; #define PG8_SCHED __builtin_amdgcn_sched_barrier(0)
; template <class Epi, class Sched>
; __device__ __forceinline__ void gemm_phase(LAS unsigned char* lds, const Gemm g, const Sched& S, const Epi& E) {
;     ...
;             PG8_WAIT_V(6); PG8_BAR; PG8_MMA(1, 1, At, B1); PG8_BAR;
;             PG8_LDB(B0, 1, 0); PG8_SCHED; PG8_LDA(At, 1, 0); PG8_STAGE(PG8_SA(0, 1), a2 + hstep, voffA);
;             PG8_WAIT_L(8); PG8_BAR; PG8_WAIT_L(0); PG8_MMA(0, 0, At, B0); PG8_BAR; PG8_SCHED;
;             PG8_LDB(B1, 1, 1); PG8_STAGE(PG8_SB(1, 0), b3, voffB);
;             PG8_BAR; PG8_WAIT_L(0); PG8_MMA(0, 1, At, B1); PG8_BAR;
;             PG8_LDA(At, 1, 1); PG8_STAGE(PG8_SA(1, 0), a3, voffA);
;             PG8_BAR; PG8_WAIT_L(0); PG8_MMA(1, 0, At, B0); PG8_BAR; PG8_SCHED;
	v_mfma_f32_16x16x32_bf16 v[44:47], v[220:223], v[144:147], v[44:47]
	v_mfma_f32_16x16x32_bf16 v[40:43], v[228:231], v[144:147], v[40:43]
	v_mfma_f32_16x16x32_bf16 v[28:31], v[220:223], v[170:173], v[28:31]
	v_mfma_f32_16x16x32_bf16 v[24:27], v[228:231], v[170:173], v[24:27]
	v_mfma_f32_16x16x32_bf16 v[12:15], v[220:223], v[204:207], v[12:15]
	v_mfma_f32_16x16x32_bf16 v[8:11], v[228:231], v[204:207], v[8:11]
	v_mfma_f32_16x16x32_bf16 v[4:7], v[220:223], v[212:215], v[4:7]
	v_mfma_f32_16x16x32_bf16 v[0:3], v[228:231], v[212:215], v[0:3]
	v_mfma_f32_16x16x32_bf16 v[44:47], v[224:227], v[166:169], v[44:47]
	v_mfma_f32_16x16x32_bf16 v[40:43], v[232:235], v[166:169], v[40:43]
	v_mfma_f32_16x16x32_bf16 v[28:31], v[224:227], v[174:177], v[28:31]
	v_mfma_f32_16x16x32_bf16 v[24:27], v[232:235], v[174:177], v[24:27]
	v_mfma_f32_16x16x32_bf16 v[12:15], v[224:227], v[208:211], v[12:15]
	v_mfma_f32_16x16x32_bf16 v[8:11], v[232:235], v[208:211], v[8:11]
	v_mfma_f32_16x16x32_bf16 v[4:7], v[224:227], v[216:219], v[4:7]
	v_mfma_f32_16x16x32_bf16 v[0:3], v[232:235], v[216:219], v[0:3]
	s_add_i32 s48, 0, 0x18000
	s_barrier
	ds_read_b128 v[128:131], v161 offset:32768
	ds_read_b128 v[132:135], v161 offset:33792
	ds_read_b128 v[136:139], v161 offset:34816
	ds_read_b128 v[140:143], v161 offset:35840
	s_add_u32 s16, s24, 0x80000
	s_addc_u32 s17, s25, 0
	s_mov_b32 m0, s35
	ds_read_b128 v[144:147], v203 offset:32768
	ds_read_b128 v[166:169], v203 offset:33792
	ds_read_b128 v[170:173], v203 offset:34816
	ds_read_b128 v[174:177], v203 offset:35840
	ds_read_b128 v[204:207], v203 offset:36864
	ds_read_b128 v[208:211], v203 offset:37888
	ds_read_b128 v[212:215], v203 offset:38912
	ds_read_b128 v[216:219], v203 offset:39936
	global_load_lds_dwordx4 v148, s[16:17]
	s_mov_b32 m0, s36
	s_nop 0
	global_load_lds_dwordx4 v160, s[16:17]
	s_waitcnt lgkmcnt(8)
	s_barrier
	s_waitcnt lgkmcnt(0)
	v_mfma_f32_16x16x32_bf16 v[124:127], v[128:131], v[144:147], v[124:127]
	v_mfma_f32_16x16x32_bf16 v[120:123], v[136:139], v[144:147], v[120:123]
	v_mfma_f32_16x16x32_bf16 v[116:119], v[128:131], v[170:173], v[116:119]
	v_mfma_f32_16x16x32_bf16 v[112:115], v[136:139], v[170:173], v[112:115]
	v_mfma_f32_16x16x32_bf16 v[100:103], v[128:131], v[204:207], v[100:103]
	v_mfma_f32_16x16x32_bf16 v[96:99], v[136:139], v[204:207], v[96:99]
	v_mfma_f32_16x16x32_bf16 v[84:87], v[128:131], v[212:215], v[84:87]
	v_mfma_f32_16x16x32_bf16 v[80:83], v[136:139], v[212:215], v[80:83]
	v_mfma_f32_16x16x32_bf16 v[124:127], v[132:135], v[166:169], v[124:127]
	v_mfma_f32_16x16x32_bf16 v[120:123], v[140:143], v[166:169], v[120:123]
	v_mfma_f32_16x16x32_bf16 v[116:119], v[132:135], v[174:177], v[116:119]
	v_mfma_f32_16x16x32_bf16 v[112:115], v[140:143], v[174:177], v[112:115]
	v_mfma_f32_16x16x32_bf16 v[100:103], v[132:135], v[208:211], v[100:103]
	v_mfma_f32_16x16x32_bf16 v[96:99], v[140:143], v[208:211], v[96:99]
	v_mfma_f32_16x16x32_bf16 v[84:87], v[132:135], v[216:219], v[84:87]
	v_mfma_f32_16x16x32_bf16 v[80:83], v[140:143], v[216:219], v[80:83]
	s_barrier
	s_add_i32 s24, 0, 0x1c000
	s_add_i32 s16, s48, s31
	s_mov_b32 m0, s16
	ds_read_b128 v[220:223], v161 offset:49152
	ds_read_b128 v[224:227], v161 offset:50176
	ds_read_b128 v[228:231], v161 offset:51200
	ds_read_b128 v[232:235], v161 offset:52224
	global_load_lds_dwordx4 v148, s[84:85]
	s_add_i32 m0, s16, 0x2000
	s_nop 0
	global_load_lds_dwordx4 v160, s[84:85]
	s_waitcnt lgkmcnt(0)
	s_barrier
	v_mfma_f32_16x16x32_bf16 v[108:111], v[220:223], v[144:147], v[108:111]
	v_mfma_f32_16x16x32_bf16 v[104:107], v[228:231], v[144:147], v[104:107]
	v_mfma_f32_16x16x32_bf16 v[92:95], v[220:223], v[170:173], v[92:95]
	v_mfma_f32_16x16x32_bf16 v[88:91], v[228:231], v[170:173], v[88:91]
	v_mfma_f32_16x16x32_bf16 v[76:79], v[220:223], v[204:207], v[76:79]
	v_mfma_f32_16x16x32_bf16 v[72:75], v[228:231], v[204:207], v[72:75]
	v_mfma_f32_16x16x32_bf16 v[68:71], v[220:223], v[212:215], v[68:71]
	v_mfma_f32_16x16x32_bf16 v[64:67], v[228:231], v[212:215], v[64:67]
	v_mfma_f32_16x16x32_bf16 v[108:111], v[224:227], v[166:169], v[108:111]
	v_mfma_f32_16x16x32_bf16 v[104:107], v[232:235], v[166:169], v[104:107]
	v_mfma_f32_16x16x32_bf16 v[92:95], v[224:227], v[174:177], v[92:95]
	v_mfma_f32_16x16x32_bf16 v[88:91], v[232:235], v[174:177], v[88:91]
	v_mfma_f32_16x16x32_bf16 v[76:79], v[224:227], v[208:211], v[76:79]
	v_mfma_f32_16x16x32_bf16 v[72:75], v[232:235], v[208:211], v[72:75]
	v_mfma_f32_16x16x32_bf16 v[68:71], v[224:227], v[216:219], v[68:71]
	v_mfma_f32_16x16x32_bf16 v[64:67], v[232:235], v[216:219], v[64:67]
	s_mov_b32 m0, s39
	s_barrier
	ds_read_b128 v[144:147], v203 offset:49152
	ds_read_b128 v[166:169], v203 offset:50176
	ds_read_b128 v[170:173], v203 offset:51200
	ds_read_b128 v[174:177], v203 offset:52224
	ds_read_b128 v[204:207], v203 offset:53248
	ds_read_b128 v[208:211], v203 offset:54272
	ds_read_b128 v[212:215], v203 offset:55296
	ds_read_b128 v[216:219], v203 offset:56320
	global_load_lds_dwordx4 v148, s[86:87]
	s_mov_b32 m0, s40
	s_nop 0
	global_load_lds_dwordx4 v160, s[86:87]
	s_waitcnt lgkmcnt(0)
	s_barrier
	v_mfma_f32_16x16x32_bf16 v[60:63], v[128:131], v[144:147], v[60:63]
	v_mfma_f32_16x16x32_bf16 v[56:59], v[136:139], v[144:147], v[56:59]
	v_mfma_f32_16x16x32_bf16 v[52:55], v[128:131], v[170:173], v[52:55]
	v_mfma_f32_16x16x32_bf16 v[48:51], v[136:139], v[170:173], v[48:51]
	v_mfma_f32_16x16x32_bf16 v[36:39], v[128:131], v[204:207], v[36:39]
	v_mfma_f32_16x16x32_bf16 v[32:35], v[136:139], v[204:207], v[32:35]
	v_mfma_f32_16x16x32_bf16 v[20:23], v[128:131], v[212:215], v[20:23]
	v_mfma_f32_16x16x32_bf16 v[16:19], v[136:139], v[212:215], v[16:19]
	v_mfma_f32_16x16x32_bf16 v[60:63], v[132:135], v[166:169], v[60:63]
	v_mfma_f32_16x16x32_bf16 v[56:59], v[140:143], v[166:169], v[56:59]
	v_mfma_f32_16x16x32_bf16 v[52:55], v[132:135], v[174:177], v[52:55]
	v_mfma_f32_16x16x32_bf16 v[48:51], v[140:143], v[174:177], v[48:51]
	v_mfma_f32_16x16x32_bf16 v[36:39], v[132:135], v[208:211], v[36:39]
	v_mfma_f32_16x16x32_bf16 v[32:35], v[140:143], v[208:211], v[32:35]
	v_mfma_f32_16x16x32_bf16 v[20:23], v[132:135], v[216:219], v[20:23]
	v_mfma_f32_16x16x32_bf16 v[16:19], v[140:143], v[216:219], v[16:19]
	s_barrier
; #define PG8_STAGE(bufoff, gbase, voff) do { _Pragma("unroll") for (int _i = 0; _i < 2; ++_i) \
;         __builtin_amdgcn_global_load_lds((const unsigned*)((const char*)(gbase) + (voff)[_i]), (LAS unsigned*)(lds + (bufoff) + ldsw + _i * 8192), 16, 0, 0); } while (0)
; #define PG8_MMA(ai, bj, At, Bt) do { __builtin_amdgcn_s_setprio(1); _Pragma("unroll") for (int m = 0; m < 4; ++m) _Pragma("unroll") for (int n = 0; n < 2; ++n) _Pragma("unroll") for (int k = 0; k < 2; ++k) \
;         acc[ai][bj][m][n] = __builtin_amdgcn_mfma_f32_16x16x32_bf16(Bt[n][k], At[m][k], acc[ai][bj][m][n], 0, 0, 0); __builtin_amdgcn_s_setprio(0); } while (0)
; #define PG8_WAIT_V(n) asm volatile("s_waitcnt vmcnt(" #n ")" ::: "memory")
; #define PG8_BAR __builtin_amdgcn_s_barrier()
;     __device__ __forceinline__ void operator()(const f32x4 (&acc)[2][2][4][2], const Unit& u, int wr, int wc, int fr, int fq) const {
;     ...
;         const float* base = (u.pm < 32) ? base_lo : base_hi;
; #pragma unroll
;         for (int ai = 0; ai < 2; ++ai) {
;             f32x4 bs[4][2][2];
; #pragma unroll
;             for (int m = 0; m < 4; ++m) { const size_t off = (size_t)(row0 + ai * HALF + m * 16) * DM + col0;
; #pragma unroll
;                 for (int bj = 0; bj < 2; ++bj)
; #pragma unroll
;                     for (int n = 0; n < 2; ++n) bs[m][bj][n] = *(const f32x4*)(base + off + bj * HALF + n * 16); }
; #pragma unroll
;             for (int m = 0; m < 4; ++m) { const size_t off = (size_t)(row0 + ai * HALF + m * 16) * DM + col0;
; #pragma unroll
;                 for (int bj = 0; bj < 2; ++bj)
; #pragma unroll
;                     for (int n = 0; n < 2; ++n) *(f32x4*)(out + off + bj * HALF + n * 16) = bs[m][bj][n] + scale * acc[ai][bj][m][n]; }
;             asm volatile("" ::: "memory");
; template <class Epi, class Sched>
; __device__ __forceinline__ void gemm_phase(LAS unsigned char* lds, const Gemm g, const Sched& S, const Epi& E) {
;     ...
;             PG8_STAGE(PG8_SB(1, 1), b3 + hstep, voffB);
;             PG8_WAIT_V(6); PG8_BAR; PG8_MMA(1, 1, At, B1); PG8_BAR;
	s_add_u32 s16, s22, 0x80080
	s_addc_u32 s17, s23, 0
	s_add_i32 s22, s24, s31
	s_mov_b32 m0, s22
	s_nop 0
	global_load_lds_dwordx4 v148, s[16:17]
	s_add_i32 m0, s22, 0x2000
	s_nop 0
	global_load_lds_dwordx4 v160, s[16:17]
	s_waitcnt vmcnt(6)
	s_barrier
	v_mfma_f32_16x16x32_bf16 v[44:47], v[220:223], v[144:147], v[44:47]
	v_mfma_f32_16x16x32_bf16 v[40:43], v[228:231], v[144:147], v[40:43]
	v_mfma_f32_16x16x32_bf16 v[28:31], v[220:223], v[170:173], v[28:31]
	v_mfma_f32_16x16x32_bf16 v[24:27], v[228:231], v[170:173], v[24:27]
	v_mfma_f32_16x16x32_bf16 v[12:15], v[220:223], v[204:207], v[12:15]
	v_mfma_f32_16x16x32_bf16 v[8:11], v[228:231], v[204:207], v[8:11]
	v_mfma_f32_16x16x32_bf16 v[4:7], v[220:223], v[212:215], v[4:7]
	v_mfma_f32_16x16x32_bf16 v[0:3], v[228:231], v[212:215], v[0:3]
	v_mfma_f32_16x16x32_bf16 v[44:47], v[224:227], v[166:169], v[44:47]
	v_mfma_f32_16x16x32_bf16 v[40:43], v[232:235], v[166:169], v[40:43]
	v_mfma_f32_16x16x32_bf16 v[28:31], v[224:227], v[174:177], v[28:31]
	v_mfma_f32_16x16x32_bf16 v[24:27], v[232:235], v[174:177], v[24:27]
	v_mfma_f32_16x16x32_bf16 v[12:15], v[224:227], v[208:211], v[12:15]
	v_mfma_f32_16x16x32_bf16 v[8:11], v[232:235], v[208:211], v[8:11]
	v_mfma_f32_16x16x32_bf16 v[4:7], v[224:227], v[216:219], v[4:7]
	v_mfma_f32_16x16x32_bf16 v[0:3], v[232:235], v[216:219], v[0:3]
	s_add_u32 s13, s13, 0x100
	s_addc_u32 s15, s15, 0
	s_cmp_ge_i32 s47, s45
	s_mov_b64 s[16:17], s[20:21]
	s_mov_b32 s22, s47
	s_barrier
	s_cbranch_scc0 .LBB0_267
	v_lshl_add_u32 v166, s46, 8, v200
	v_lshl_or_b32 v168, s44, 8, v202
	s_mov_b64 s[16:17], -1
	s_cmp_lt_i32 s82, 0
	v_ashrrev_i32_e32 v169, 31, v168
	v_ashrrev_i32_e32 v167, 31, v166
	s_cbranch_scc0 .LBB0_270
	v_lshlrev_b64 v[170:171], 2, v[168:169]
	v_lshl_add_u64 v[172:173], s[60:61], 0, v[170:171]
	v_lshlrev_b64 v[174:175], 13, v[166:167]
	v_lshl_add_u64 v[128:129], v[172:173], 0, v[174:175]
	global_load_dwordx4 v[204:207], v[128:129], off
	global_load_dwordx4 v[208:211], v[128:129], off offset:64
	global_load_dwordx4 v[212:215], v[128:129], off offset:512
	global_load_dwordx4 v[216:219], v[128:129], off offset:576
	v_or_b32_e32 v128, 16, v166
	v_ashrrev_i32_e32 v129, 31, v128
	v_lshlrev_b64 v[188:189], 13, v[128:129]
	v_lshl_add_u64 v[128:129], v[172:173], 0, v[188:189]
	global_load_dwordx4 v[220:223], v[128:129], off
	global_load_dwordx4 v[224:227], v[128:129], off offset:64
	global_load_dwordx4 v[228:231], v[128:129], off offset:512
	global_load_dwordx4 v[232:235], v[128:129], off offset:576
	v_or_b32_e32 v128, 32, v166
	v_ashrrev_i32_e32 v129, 31, v128
	v_lshlrev_b64 v[190:191], 13, v[128:129]
	v_lshl_add_u64 v[128:129], v[172:173], 0, v[190:191]
	global_load_dwordx4 v[236:239], v[128:129], off
	global_load_dwordx4 v[240:243], v[128:129], off offset:64
	global_load_dwordx4 v[144:147], v[128:129], off offset:512
	global_load_dwordx4 v[140:143], v[128:129], off offset:576
	v_or_b32_e32 v128, 48, v166
	v_ashrrev_i32_e32 v129, 31, v128
	v_lshlrev_b64 v[176:177], 13, v[128:129]
	v_lshl_add_u64 v[128:129], v[172:173], 0, v[176:177]
	global_load_dwordx4 v[244:247], v[128:129], off
	global_load_dwordx4 v[136:139], v[128:129], off offset:64
	global_load_dwordx4 v[132:135], v[128:129], off offset:512
	s_nop 0
	global_load_dwordx4 v[128:131], v[128:129], off offset:576
	v_lshl_add_u64 v[248:249], s[60:61], 0, v[174:175]
	v_lshl_add_u64 v[248:249], v[248:249], 0, v[170:171]
	v_lshl_add_u64 v[188:189], s[60:61], 0, v[188:189]
	v_lshl_add_u64 v[188:189], v[188:189], 0, v[170:171]
	s_mov_b64 s[16:17], 0x100000
	s_waitcnt vmcnt(0)
	v_pk_add_f32 v[206:207], v[206:207], v[126:127]
	v_pk_add_f32 v[204:205], v[204:205], v[124:125]
	global_store_dwordx4 v[248:249], v[204:207], off
	v_pk_add_f32 v[146:147], v[146:147], v[78:79]
	s_nop 0
	v_pk_add_f32 v[206:207], v[210:211], v[122:123]
	v_pk_add_f32 v[204:205], v[208:209], v[120:121]
	global_store_dwordx4 v[248:249], v[204:207], off offset:64
	v_pk_add_f32 v[144:145], v[144:145], v[76:77]
	v_pk_add_f32 v[142:143], v[142:143], v[74:75]
	v_pk_add_f32 v[206:207], v[214:215], v[110:111]
	v_pk_add_f32 v[204:205], v[212:213], v[108:109]
	global_store_dwordx4 v[248:249], v[204:207], off offset:512
	v_pk_add_f32 v[140:141], v[140:141], v[72:73]
	v_pk_add_f32 v[138:139], v[138:139], v[82:83]
	v_pk_add_f32 v[206:207], v[218:219], v[106:107]
	v_pk_add_f32 v[204:205], v[216:217], v[104:105]
	global_store_dwordx4 v[248:249], v[204:207], off offset:576
	v_pk_add_f32 v[136:137], v[136:137], v[80:81]
	v_pk_add_f32 v[134:135], v[134:135], v[70:71]
	v_pk_add_f32 v[206:207], v[222:223], v[118:119]
	v_pk_add_f32 v[204:205], v[220:221], v[116:117]
	global_store_dwordx4 v[188:189], v[204:207], off
	v_pk_add_f32 v[132:133], v[132:133], v[68:69]
	v_pk_add_f32 v[130:131], v[130:131], v[66:67]
	v_pk_add_f32 v[206:207], v[226:227], v[114:115]
	v_pk_add_f32 v[204:205], v[224:225], v[112:113]
	global_store_dwordx4 v[188:189], v[204:207], off offset:64
	v_pk_add_f32 v[128:129], v[128:129], v[64:65]
	s_nop 0
	v_pk_add_f32 v[206:207], v[230:231], v[94:95]
	v_pk_add_f32 v[204:205], v[228:229], v[92:93]
	global_store_dwordx4 v[188:189], v[204:207], off offset:512
	s_nop 1
	v_pk_add_f32 v[206:207], v[234:235], v[90:91]
	v_pk_add_f32 v[204:205], v[232:233], v[88:89]
	global_store_dwordx4 v[188:189], v[204:207], off offset:576
;     __device__ __forceinline__ void operator()(const f32x4 (&acc)[2][2][4][2], const Unit& u, int wr, int wc, int fr, int fq) const {
;     ...
;         const float* base = (u.pm < 32) ? base_lo : base_hi;
; #pragma unroll
;         for (int ai = 0; ai < 2; ++ai) {
;             f32x4 bs[4][2][2];
; #pragma unroll
;             for (int m = 0; m < 4; ++m) { const size_t off = (size_t)(row0 + ai * HALF + m * 16) * DM + col0;
; #pragma unroll
;                 for (int bj = 0; bj < 2; ++bj)
; #pragma unroll
;                     for (int n = 0; n < 2; ++n) bs[m][bj][n] = *(const f32x4*)(base + off + bj * HALF + n * 16); }
; #pragma unroll
;             for (int m = 0; m < 4; ++m) { const size_t off = (size_t)(row0 + ai * HALF + m * 16) * DM + col0;
; #pragma unroll
;                 for (int bj = 0; bj < 2; ++bj)
; #pragma unroll
;                     for (int n = 0; n < 2; ++n) *(f32x4*)(out + off + bj * HALF + n * 16) = bs[m][bj][n] + scale * acc[ai][bj][m][n]; }
;             asm volatile("" ::: "memory");
	v_lshl_add_u64 v[188:189], s[60:61], 0, v[190:191]
	v_lshl_add_u64 v[188:189], v[188:189], 0, v[170:171]
	v_pk_add_f32 v[206:207], v[238:239], v[102:103]
	v_pk_add_f32 v[204:205], v[236:237], v[100:101]
	global_store_dwordx4 v[188:189], v[144:147], off offset:512
	global_store_dwordx4 v[188:189], v[204:207], off
	global_store_dwordx4 v[188:189], v[140:143], off offset:576
	v_lshl_add_u64 v[144:145], s[60:61], 0, v[176:177]
	v_pk_add_f32 v[206:207], v[242:243], v[98:99]
	v_pk_add_f32 v[204:205], v[240:241], v[96:97]
	v_pk_add_f32 v[142:143], v[246:247], v[86:87]
	v_pk_add_f32 v[140:141], v[244:245], v[84:85]
	v_lshl_add_u64 v[144:145], v[144:145], 0, v[170:171]
	global_store_dwordx4 v[188:189], v[204:207], off offset:64
	global_store_dwordx4 v[144:145], v[140:143], off
	global_store_dwordx4 v[144:145], v[136:139], off offset:64
	global_store_dwordx4 v[144:145], v[132:135], off offset:512
	global_store_dwordx4 v[144:145], v[128:131], off offset:576
	v_lshl_add_u64 v[146:147], v[174:175], 0, s[16:17]
	s_mov_b64 s[16:17], 0x120000
	v_lshl_add_u64 v[128:129], v[172:173], 0, v[146:147]
	global_load_dwordx4 v[142:145], v[128:129], off
	global_load_dwordx4 v[204:207], v[128:129], off offset:64
	global_load_dwordx4 v[208:211], v[128:129], off offset:512
	global_load_dwordx4 v[212:215], v[128:129], off offset:576
	v_lshl_add_u64 v[176:177], v[174:175], 0, s[16:17]
	v_lshl_add_u64 v[128:129], v[172:173], 0, v[176:177]
	global_load_dwordx4 v[216:219], v[128:129], off
	global_load_dwordx4 v[220:223], v[128:129], off offset:64
	global_load_dwordx4 v[224:227], v[128:129], off offset:512
	global_load_dwordx4 v[228:231], v[128:129], off offset:576
	s_mov_b64 s[16:17], 0x140000
	v_lshl_add_u64 v[188:189], v[174:175], 0, s[16:17]
	s_mov_b64 s[16:17], 0x160000
	v_lshl_add_u64 v[128:129], v[172:173], 0, v[188:189]
	v_lshl_add_u64 v[140:141], v[174:175], 0, s[16:17]
	global_load_dwordx4 v[232:235], v[128:129], off
	global_load_dwordx4 v[236:239], v[128:129], off offset:64
	global_load_dwordx4 v[240:243], v[128:129], off offset:512
	global_load_dwordx4 v[244:247], v[128:129], off offset:576
	v_lshl_add_u64 v[128:129], v[172:173], 0, v[140:141]
	global_load_dwordx4 v[172:175], v[128:129], off
	global_load_dwordx4 v[136:139], v[128:129], off offset:64
	global_load_dwordx4 v[132:135], v[128:129], off offset:512
	s_nop 0
	global_load_dwordx4 v[128:131], v[128:129], off offset:576
	v_lshl_add_u64 v[146:147], s[60:61], 0, v[146:147]
	v_lshl_add_u64 v[146:147], v[146:147], 0, v[170:171]
	v_lshl_add_u64 v[140:141], s[60:61], 0, v[140:141]
	v_lshl_add_u64 v[140:141], v[140:141], 0, v[170:171]
	s_mov_b64 s[16:17], 0
	s_waitcnt vmcnt(0)
	v_pk_add_f32 v[144:145], v[62:63], v[144:145]
	v_pk_add_f32 v[142:143], v[60:61], v[142:143]
	global_store_dwordx4 v[146:147], v[142:145], off
	v_pk_add_f32 v[138:139], v[18:19], v[138:139]
	s_nop 0
	v_pk_add_f32 v[144:145], v[58:59], v[206:207]
	v_pk_add_f32 v[142:143], v[56:57], v[204:205]
	global_store_dwordx4 v[146:147], v[142:145], off offset:64
	v_pk_add_f32 v[136:137], v[16:17], v[136:137]
	v_pk_add_f32 v[134:135], v[6:7], v[134:135]
	v_pk_add_f32 v[144:145], v[46:47], v[210:211]
	v_pk_add_f32 v[142:143], v[44:45], v[208:209]
	global_store_dwordx4 v[146:147], v[142:145], off offset:512
	v_pk_add_f32 v[132:133], v[4:5], v[132:133]
	v_pk_add_f32 v[130:131], v[2:3], v[130:131]
	v_pk_add_f32 v[144:145], v[42:43], v[214:215]
	v_pk_add_f32 v[142:143], v[40:41], v[212:213]
	global_store_dwordx4 v[146:147], v[142:145], off offset:576
	v_lshl_add_u64 v[146:147], s[60:61], 0, v[176:177]
	v_lshl_add_u64 v[146:147], v[146:147], 0, v[170:171]
	v_pk_add_f32 v[144:145], v[54:55], v[218:219]
	v_pk_add_f32 v[142:143], v[52:53], v[216:217]
	global_store_dwordx4 v[146:147], v[142:145], off
	v_pk_add_f32 v[128:129], v[0:1], v[128:129]
	global_store_dwordx4 v[140:141], v[136:139], off offset:64
	v_pk_add_f32 v[144:145], v[50:51], v[222:223]
	v_pk_add_f32 v[142:143], v[48:49], v[220:221]
	global_store_dwordx4 v[146:147], v[142:145], off offset:64
	global_store_dwordx4 v[140:141], v[132:135], off offset:512
	global_store_dwordx4 v[140:141], v[128:131], off offset:576
	v_pk_add_f32 v[144:145], v[30:31], v[226:227]
	v_pk_add_f32 v[142:143], v[28:29], v[224:225]
	global_store_dwordx4 v[146:147], v[142:145], off offset:512
	s_nop 1
	v_pk_add_f32 v[144:145], v[26:27], v[230:231]
	v_pk_add_f32 v[142:143], v[24:25], v[228:229]
	global_store_dwordx4 v[146:147], v[142:145], off offset:576
	v_lshl_add_u64 v[146:147], s[60:61], 0, v[188:189]
	v_lshl_add_u64 v[146:147], v[146:147], 0, v[170:171]
	v_pk_add_f32 v[144:145], v[38:39], v[234:235]
	v_pk_add_f32 v[142:143], v[36:37], v[232:233]
	global_store_dwordx4 v[146:147], v[142:145], off
	s_nop 1
	v_pk_add_f32 v[144:145], v[34:35], v[238:239]
	v_pk_add_f32 v[142:143], v[32:33], v[236:237]
	global_store_dwordx4 v[146:147], v[142:145], off offset:64
	s_nop 1
	v_pk_add_f32 v[144:145], v[14:15], v[242:243]
	v_pk_add_f32 v[142:143], v[12:13], v[240:241]
	global_store_dwordx4 v[146:147], v[142:145], off offset:512
	s_nop 1
	v_pk_add_f32 v[144:145], v[10:11], v[246:247]
	v_pk_add_f32 v[142:143], v[8:9], v[244:245]
	global_store_dwordx4 v[146:147], v[142:145], off offset:576
	s_nop 1
	v_pk_add_f32 v[144:145], v[22:23], v[174:175]
	v_pk_add_f32 v[142:143], v[20:21], v[172:173]
	global_store_dwordx4 v[140:141], v[142:145], off
